# GEMM K-loops: setprio raise moved before the pre-MFMA barrier and the drop after the post-MFMA barrier (MFMA segment has no scalar slots)
# speedup vs baseline: 1.0090x; 1.0013x over previous
.LBB0_131:
	s_add_u32 s28, s8, s10
	s_addc_u32 s29, s9, s11
	s_add_u32 s34, s28, 0x100
	s_addc_u32 s35, s29, 0
	s_add_u32 s30, s70, s10
	s_addc_u32 s31, s71, s11
	s_add_u32 s28, s28, 0x180
	s_addc_u32 s29, s29, 0
	s_add_i32 s73, 0, 0x10000
	s_add_i32 s76, 0, 0x14000
	v_add_u32_e32 v146, s73, v166
	ds_read_b128 v[148:151], v146
	ds_read_b128 v[152:155], v146 offset:1024
	ds_read_b128 v[156:159], v146 offset:2048
	ds_read_b128 v[160:163], v146 offset:3072
	v_add_u32_e32 v146, s76, v166
	ds_read_b128 v[172:175], v146
	ds_read_b128 v[176:179], v146 offset:1024
	ds_read_b128 v[180:183], v146 offset:2048
	ds_read_b128 v[184:187], v146 offset:3072
	s_cmpk_eq_i32 s10, 0x700
	s_cselect_b32 s29, s69, s29
	s_cselect_b32 s28, s68, s28
	s_cselect_b32 s31, s21, s31
	s_cselect_b32 s30, s59, s30
	s_cselect_b32 s35, s23, s35
	s_cselect_b32 s34, s58, s34
	v_lshl_add_u64 v[164:165], v[142:143], 0, s[10:11]
	s_add_i32 m0, s41, 0xc000
	ds_read_b128 v[188:191], v171
	ds_read_b128 v[202:205], v171 offset:1024
	ds_read_b128 v[206:209], v171 offset:2048
	ds_read_b128 v[210:213], v171 offset:3072
	ds_read_b128 v[214:217], v171 offset:4096
	ds_read_b128 v[218:221], v171 offset:5120
	ds_read_b128 v[222:225], v171 offset:6144
	ds_read_b128 v[226:229], v171 offset:7168
	global_load_lds_dwordx4 v[164:165], off
	v_lshl_add_u64 v[164:165], v[144:145], 0, s[10:11]
	s_add_i32 m0, s41, 0xe000
	s_nop 0
	global_load_lds_dwordx4 v[164:165], off
	s_waitcnt vmcnt(8)
	s_waitcnt lgkmcnt(0)
	s_setprio 1
	s_barrier
	v_mfma_f32_16x16x32_bf16 v[126:129], v[148:151], v[188:191], v[126:129]
	v_mfma_f32_16x16x32_bf16 v[122:125], v[156:159], v[188:191], v[122:125]
	v_mfma_f32_16x16x32_bf16 v[110:113], v[148:151], v[206:209], v[110:113]
	v_mfma_f32_16x16x32_bf16 v[106:109], v[156:159], v[206:209], v[106:109]
	v_mfma_f32_16x16x32_bf16 v[94:97], v[148:151], v[214:217], v[94:97]
	v_mfma_f32_16x16x32_bf16 v[90:93], v[156:159], v[214:217], v[90:93]
	v_mfma_f32_16x16x32_bf16 v[78:81], v[148:151], v[222:225], v[78:81]
	v_mfma_f32_16x16x32_bf16 v[74:77], v[156:159], v[222:225], v[74:77]
	v_mfma_f32_16x16x32_bf16 v[126:129], v[152:155], v[202:205], v[126:129]
	v_mfma_f32_16x16x32_bf16 v[122:125], v[160:163], v[202:205], v[122:125]
	v_mfma_f32_16x16x32_bf16 v[110:113], v[152:155], v[210:213], v[110:113]
	v_mfma_f32_16x16x32_bf16 v[106:109], v[160:163], v[210:213], v[106:109]
	v_mfma_f32_16x16x32_bf16 v[94:97], v[152:155], v[218:221], v[94:97]
	v_mfma_f32_16x16x32_bf16 v[90:93], v[160:163], v[218:221], v[90:93]
	v_mfma_f32_16x16x32_bf16 v[78:81], v[152:155], v[226:229], v[78:81]
	v_mfma_f32_16x16x32_bf16 v[74:77], v[160:163], v[226:229], v[74:77]
	v_mfma_f32_16x16x32_bf16 v[118:121], v[172:175], v[188:191], v[118:121]
	v_mfma_f32_16x16x32_bf16 v[114:117], v[180:183], v[188:191], v[114:117]
	v_mfma_f32_16x16x32_bf16 v[102:105], v[172:175], v[206:209], v[102:105]
	v_mfma_f32_16x16x32_bf16 v[98:101], v[180:183], v[206:209], v[98:101]
	v_mfma_f32_16x16x32_bf16 v[86:89], v[172:175], v[214:217], v[86:89]
	v_mfma_f32_16x16x32_bf16 v[82:85], v[180:183], v[214:217], v[82:85]
	v_mfma_f32_16x16x32_bf16 v[70:73], v[172:175], v[222:225], v[70:73]
	v_mfma_f32_16x16x32_bf16 v[66:69], v[180:183], v[222:225], v[66:69]
	v_mfma_f32_16x16x32_bf16 v[118:121], v[176:179], v[202:205], v[118:121]
	v_mfma_f32_16x16x32_bf16 v[114:117], v[184:187], v[202:205], v[114:117]
	v_mfma_f32_16x16x32_bf16 v[102:105], v[176:179], v[210:213], v[102:105]
	v_mfma_f32_16x16x32_bf16 v[98:101], v[184:187], v[210:213], v[98:101]
	v_mfma_f32_16x16x32_bf16 v[86:89], v[176:179], v[218:221], v[86:89]
	v_mfma_f32_16x16x32_bf16 v[82:85], v[184:187], v[218:221], v[82:85]
	v_mfma_f32_16x16x32_bf16 v[70:73], v[176:179], v[226:229], v[70:73]
	v_mfma_f32_16x16x32_bf16 v[66:69], v[184:187], v[226:229], v[66:69]
	s_barrier
	s_setprio 0
	s_add_i32 s73, s73, s40
	v_lshl_add_u64 v[164:165], s[30:31], 0, v[134:135]
	s_mov_b32 m0, s73
	ds_read_b128 v[188:191], v171 offset:16384
	ds_read_b128 v[202:205], v171 offset:17408
	ds_read_b128 v[206:209], v171 offset:18432
	ds_read_b128 v[210:213], v171 offset:19456
	ds_read_b128 v[214:217], v171 offset:20480
	ds_read_b128 v[218:221], v171 offset:21504
	ds_read_b128 v[222:225], v171 offset:22528
	ds_read_b128 v[226:229], v171 offset:23552
	global_load_lds_dwordx4 v[164:165], off
	s_add_i32 m0, s73, 0x2000
	s_add_u32 s74, s30, 0x40000
	v_lshl_add_u64 v[192:193], s[30:31], 0, v[130:131]
	s_addc_u32 s75, s31, 0
	s_add_i32 s73, s76, s40
	global_load_lds_dwordx4 v[192:193], off
	v_lshl_add_u64 v[194:195], s[74:75], 0, v[134:135]
	s_mov_b32 m0, s73
	s_nop 0
	global_load_lds_dwordx4 v[194:195], off
	v_lshl_add_u64 v[194:195], s[74:75], 0, v[130:131]
	s_add_i32 m0, s73, 0x2000
	s_nop 0
	global_load_lds_dwordx4 v[194:195], off
	v_lshl_add_u64 v[194:195], s[34:35], 0, v[136:137]
	s_mov_b32 m0, s41
	s_nop 0
	global_load_lds_dwordx4 v[194:195], off
	v_lshl_add_u64 v[194:195], s[34:35], 0, v[132:133]
	s_mov_b32 m0, s42
	s_nop 0
	global_load_lds_dwordx4 v[194:195], off
	s_waitcnt vmcnt(8)
	s_waitcnt lgkmcnt(0)
	s_setprio 1
	s_barrier
	v_mfma_f32_16x16x32_bf16 v[62:65], v[148:151], v[188:191], v[62:65]
	v_mfma_f32_16x16x32_bf16 v[58:61], v[156:159], v[188:191], v[58:61]
	v_mfma_f32_16x16x32_bf16 v[46:49], v[148:151], v[206:209], v[46:49]
	v_mfma_f32_16x16x32_bf16 v[42:45], v[156:159], v[206:209], v[42:45]
	v_mfma_f32_16x16x32_bf16 v[30:33], v[148:151], v[214:217], v[30:33]
	v_mfma_f32_16x16x32_bf16 v[26:29], v[156:159], v[214:217], v[26:29]
	v_mfma_f32_16x16x32_bf16 v[14:17], v[148:151], v[222:225], v[14:17]
	v_mfma_f32_16x16x32_bf16 v[10:13], v[156:159], v[222:225], v[10:13]
	v_mfma_f32_16x16x32_bf16 v[62:65], v[152:155], v[202:205], v[62:65]
	v_mfma_f32_16x16x32_bf16 v[58:61], v[160:163], v[202:205], v[58:61]
	v_mfma_f32_16x16x32_bf16 v[46:49], v[152:155], v[210:213], v[46:49]
	v_mfma_f32_16x16x32_bf16 v[42:45], v[160:163], v[210:213], v[42:45]
	v_mfma_f32_16x16x32_bf16 v[30:33], v[152:155], v[218:221], v[30:33]
	v_mfma_f32_16x16x32_bf16 v[26:29], v[160:163], v[218:221], v[26:29]
	v_mfma_f32_16x16x32_bf16 v[14:17], v[152:155], v[226:229], v[14:17]
	v_mfma_f32_16x16x32_bf16 v[10:13], v[160:163], v[226:229], v[10:13]
	v_mfma_f32_16x16x32_bf16 v[54:57], v[172:175], v[188:191], v[54:57]
	v_mfma_f32_16x16x32_bf16 v[50:53], v[180:183], v[188:191], v[50:53]
	v_mfma_f32_16x16x32_bf16 v[38:41], v[172:175], v[206:209], v[38:41]
	v_mfma_f32_16x16x32_bf16 v[34:37], v[180:183], v[206:209], v[34:37]
	v_mfma_f32_16x16x32_bf16 v[22:25], v[172:175], v[214:217], v[22:25]
	v_mfma_f32_16x16x32_bf16 v[18:21], v[180:183], v[214:217], v[18:21]
	v_mfma_f32_16x16x32_bf16 v[6:9], v[172:175], v[222:225], v[6:9]
	v_mfma_f32_16x16x32_bf16 v[2:5], v[180:183], v[222:225], v[2:5]
	v_mfma_f32_16x16x32_bf16 v[54:57], v[176:179], v[202:205], v[54:57]
	v_mfma_f32_16x16x32_bf16 v[50:53], v[184:187], v[202:205], v[50:53]
	v_mfma_f32_16x16x32_bf16 v[38:41], v[176:179], v[210:213], v[38:41]
	v_mfma_f32_16x16x32_bf16 v[34:37], v[184:187], v[210:213], v[34:37]
	v_mfma_f32_16x16x32_bf16 v[22:25], v[176:179], v[218:221], v[22:25]
	v_mfma_f32_16x16x32_bf16 v[18:21], v[184:187], v[218:221], v[18:21]
	v_mfma_f32_16x16x32_bf16 v[6:9], v[176:179], v[226:229], v[6:9]
	v_mfma_f32_16x16x32_bf16 v[2:5], v[184:187], v[226:229], v[2:5]
	s_barrier
	s_setprio 0
	s_add_i32 s73, 0, 0x18000
	v_add_u32_e32 v146, s73, v166
	s_add_i32 s74, 0, 0x1c000
	ds_read_b128 v[148:151], v146
	ds_read_b128 v[152:155], v146 offset:1024
	ds_read_b128 v[156:159], v146 offset:2048
	ds_read_b128 v[160:163], v146 offset:3072
	v_add_u32_e32 v146, s74, v166
	ds_read_b128 v[172:175], v146
	ds_read_b128 v[176:179], v146 offset:1024
	ds_read_b128 v[180:183], v146 offset:2048
	ds_read_b128 v[184:187], v146 offset:3072
	s_add_u32 s34, s34, 0x40000
	s_addc_u32 s35, s35, 0
	s_mov_b32 m0, s43
	v_lshl_add_u64 v[194:195], s[34:35], 0, v[136:137]
	ds_read_b128 v[188:191], v171 offset:32768
	ds_read_b128 v[202:205], v171 offset:33792
	ds_read_b128 v[206:209], v171 offset:34816
	ds_read_b128 v[210:213], v171 offset:35840
	ds_read_b128 v[214:217], v171 offset:36864
	ds_read_b128 v[218:221], v171 offset:37888
	ds_read_b128 v[222:225], v171 offset:38912
	ds_read_b128 v[226:229], v171 offset:39936
	global_load_lds_dwordx4 v[194:195], off
	v_lshl_add_u64 v[194:195], s[34:35], 0, v[132:133]
	s_mov_b32 m0, s44
	s_nop 0
	global_load_lds_dwordx4 v[194:195], off
	s_waitcnt vmcnt(8)
	s_waitcnt lgkmcnt(0)
	s_setprio 1
	s_barrier
	v_mfma_f32_16x16x32_bf16 v[126:129], v[148:151], v[188:191], v[126:129]
	v_mfma_f32_16x16x32_bf16 v[122:125], v[156:159], v[188:191], v[122:125]
	v_mfma_f32_16x16x32_bf16 v[110:113], v[148:151], v[206:209], v[110:113]
	v_mfma_f32_16x16x32_bf16 v[106:109], v[156:159], v[206:209], v[106:109]
	v_mfma_f32_16x16x32_bf16 v[94:97], v[148:151], v[214:217], v[94:97]
	v_mfma_f32_16x16x32_bf16 v[90:93], v[156:159], v[214:217], v[90:93]
	v_mfma_f32_16x16x32_bf16 v[78:81], v[148:151], v[222:225], v[78:81]
	v_mfma_f32_16x16x32_bf16 v[74:77], v[156:159], v[222:225], v[74:77]
	v_mfma_f32_16x16x32_bf16 v[126:129], v[152:155], v[202:205], v[126:129]
	v_mfma_f32_16x16x32_bf16 v[122:125], v[160:163], v[202:205], v[122:125]
	v_mfma_f32_16x16x32_bf16 v[110:113], v[152:155], v[210:213], v[110:113]
	v_mfma_f32_16x16x32_bf16 v[106:109], v[160:163], v[210:213], v[106:109]
	v_mfma_f32_16x16x32_bf16 v[94:97], v[152:155], v[218:221], v[94:97]
	v_mfma_f32_16x16x32_bf16 v[90:93], v[160:163], v[218:221], v[90:93]
	v_mfma_f32_16x16x32_bf16 v[78:81], v[152:155], v[226:229], v[78:81]
	v_mfma_f32_16x16x32_bf16 v[74:77], v[160:163], v[226:229], v[74:77]
	v_mfma_f32_16x16x32_bf16 v[118:121], v[172:175], v[188:191], v[118:121]
	v_mfma_f32_16x16x32_bf16 v[114:117], v[180:183], v[188:191], v[114:117]
	v_mfma_f32_16x16x32_bf16 v[102:105], v[172:175], v[206:209], v[102:105]
	v_mfma_f32_16x16x32_bf16 v[98:101], v[180:183], v[206:209], v[98:101]
	v_mfma_f32_16x16x32_bf16 v[86:89], v[172:175], v[214:217], v[86:89]
	v_mfma_f32_16x16x32_bf16 v[82:85], v[180:183], v[214:217], v[82:85]
	v_mfma_f32_16x16x32_bf16 v[70:73], v[172:175], v[222:225], v[70:73]
	v_mfma_f32_16x16x32_bf16 v[66:69], v[180:183], v[222:225], v[66:69]
	v_mfma_f32_16x16x32_bf16 v[118:121], v[176:179], v[202:205], v[118:121]
	v_mfma_f32_16x16x32_bf16 v[114:117], v[184:187], v[202:205], v[114:117]
	v_mfma_f32_16x16x32_bf16 v[102:105], v[176:179], v[210:213], v[102:105]
	v_mfma_f32_16x16x32_bf16 v[98:101], v[184:187], v[210:213], v[98:101]
	v_mfma_f32_16x16x32_bf16 v[86:89], v[176:179], v[218:221], v[86:89]
	v_mfma_f32_16x16x32_bf16 v[82:85], v[184:187], v[218:221], v[82:85]
	v_mfma_f32_16x16x32_bf16 v[70:73], v[176:179], v[226:229], v[70:73]
	v_mfma_f32_16x16x32_bf16 v[66:69], v[184:187], v[226:229], v[66:69]
	s_barrier
	s_setprio 0
	s_add_i32 s34, s73, s40
	v_lshl_add_u64 v[164:165], v[164:165], 0, s[90:91]
	s_mov_b32 m0, s34
	ds_read_b128 v[188:191], v171 offset:49152
	ds_read_b128 v[202:205], v171 offset:50176
	ds_read_b128 v[206:209], v171 offset:51200
	ds_read_b128 v[210:213], v171 offset:52224
	ds_read_b128 v[214:217], v171 offset:53248
	ds_read_b128 v[218:221], v171 offset:54272
	ds_read_b128 v[222:225], v171 offset:55296
	ds_read_b128 v[226:229], v171 offset:56320
	global_load_lds_dwordx4 v[164:165], off
	s_add_i32 m0, s34, 0x2000
	s_add_u32 s30, s30, 0x40080
	v_lshl_add_u64 v[164:165], v[192:193], 0, s[90:91]
	s_addc_u32 s31, s31, 0
	s_add_i32 s34, s74, s40
	global_load_lds_dwordx4 v[164:165], off
	v_lshl_add_u64 v[164:165], s[30:31], 0, v[134:135]
	s_mov_b32 m0, s34
	s_nop 0
	global_load_lds_dwordx4 v[164:165], off
	v_lshl_add_u64 v[164:165], s[30:31], 0, v[130:131]
	s_add_i32 m0, s34, 0x2000
	s_nop 0
	global_load_lds_dwordx4 v[164:165], off
	v_lshl_add_u64 v[164:165], s[28:29], 0, v[136:137]
	s_mov_b32 m0, s45
	s_nop 0
	global_load_lds_dwordx4 v[164:165], off
	v_lshl_add_u64 v[164:165], s[28:29], 0, v[132:133]
	s_mov_b32 m0, s51
	s_nop 0
	global_load_lds_dwordx4 v[164:165], off
	s_waitcnt vmcnt(8)
	s_waitcnt lgkmcnt(0)
	s_setprio 1
	s_barrier
	v_mfma_f32_16x16x32_bf16 v[62:65], v[148:151], v[188:191], v[62:65]
	v_mfma_f32_16x16x32_bf16 v[58:61], v[156:159], v[188:191], v[58:61]
	v_mfma_f32_16x16x32_bf16 v[46:49], v[148:151], v[206:209], v[46:49]
	v_mfma_f32_16x16x32_bf16 v[42:45], v[156:159], v[206:209], v[42:45]
	v_mfma_f32_16x16x32_bf16 v[30:33], v[148:151], v[214:217], v[30:33]
	v_mfma_f32_16x16x32_bf16 v[26:29], v[156:159], v[214:217], v[26:29]
	v_mfma_f32_16x16x32_bf16 v[14:17], v[148:151], v[222:225], v[14:17]
	v_mfma_f32_16x16x32_bf16 v[10:13], v[156:159], v[222:225], v[10:13]
	v_mfma_f32_16x16x32_bf16 v[62:65], v[152:155], v[202:205], v[62:65]
	v_mfma_f32_16x16x32_bf16 v[58:61], v[160:163], v[202:205], v[58:61]
	v_mfma_f32_16x16x32_bf16 v[46:49], v[152:155], v[210:213], v[46:49]
	v_mfma_f32_16x16x32_bf16 v[42:45], v[160:163], v[210:213], v[42:45]
	v_mfma_f32_16x16x32_bf16 v[30:33], v[152:155], v[218:221], v[30:33]
	v_mfma_f32_16x16x32_bf16 v[26:29], v[160:163], v[218:221], v[26:29]
	v_mfma_f32_16x16x32_bf16 v[14:17], v[152:155], v[226:229], v[14:17]
	v_mfma_f32_16x16x32_bf16 v[10:13], v[160:163], v[226:229], v[10:13]
	v_mfma_f32_16x16x32_bf16 v[54:57], v[172:175], v[188:191], v[54:57]
	v_mfma_f32_16x16x32_bf16 v[50:53], v[180:183], v[188:191], v[50:53]
	v_mfma_f32_16x16x32_bf16 v[38:41], v[172:175], v[206:209], v[38:41]
	v_mfma_f32_16x16x32_bf16 v[34:37], v[180:183], v[206:209], v[34:37]
	v_mfma_f32_16x16x32_bf16 v[22:25], v[172:175], v[214:217], v[22:25]
	v_mfma_f32_16x16x32_bf16 v[18:21], v[180:183], v[214:217], v[18:21]
	v_mfma_f32_16x16x32_bf16 v[6:9], v[172:175], v[222:225], v[6:9]
	v_mfma_f32_16x16x32_bf16 v[2:5], v[180:183], v[222:225], v[2:5]
	v_mfma_f32_16x16x32_bf16 v[54:57], v[176:179], v[202:205], v[54:57]
	v_mfma_f32_16x16x32_bf16 v[50:53], v[184:187], v[202:205], v[50:53]
	v_mfma_f32_16x16x32_bf16 v[38:41], v[176:179], v[210:213], v[38:41]
	v_mfma_f32_16x16x32_bf16 v[34:37], v[184:187], v[210:213], v[34:37]
	v_mfma_f32_16x16x32_bf16 v[22:25], v[176:179], v[218:221], v[22:25]
	v_mfma_f32_16x16x32_bf16 v[18:21], v[184:187], v[218:221], v[18:21]
	v_mfma_f32_16x16x32_bf16 v[6:9], v[176:179], v[226:229], v[6:9]
	v_mfma_f32_16x16x32_bf16 v[2:5], v[184:187], v[226:229], v[2:5]
	s_barrier
	s_setprio 0
	s_add_i32 s72, s72, 2
	s_add_u32 s10, s10, 0x100
	s_addc_u32 s11, s11, 0
	s_cmp_gt_u32 s72, 13
	s_cbranch_scc0 .LBB0_131
	s_and_b64 vcc, exec, s[18:19]
	s_cbranch_vccz .LBB0_134
	s_barrier

.LBB0_345:
	s_add_u32 s34, s28, s30
	s_addc_u32 s35, s29, s31
	s_add_u32 s38, s34, 0x100
	s_addc_u32 s39, s35, 0
	s_add_u32 s36, s75, s30
	s_addc_u32 s37, s76, s31
	s_add_u32 s34, s34, 0x180
	s_addc_u32 s35, s35, 0
	s_add_i32 s85, 0, 0x10000
	s_add_i32 vcc_lo, 0, 0x14000
	v_add_u32_e32 v0, s85, v152
	ds_read_b128 v[148:151], v0
	ds_read_b128 v[154:157], v0 offset:1024
	ds_read_b128 v[158:161], v0 offset:2048
	ds_read_b128 v[162:165], v0 offset:3072
	v_add_u32_e32 v0, vcc_lo, v152
	ds_read_b128 v[166:169], v0
	ds_read_b128 v[170:173], v0 offset:1024
	ds_read_b128 v[174:177], v0 offset:2048
	ds_read_b128 v[178:181], v0 offset:3072
	s_cmpk_eq_i32 s30, 0x700
	s_cselect_b32 s35, s74, s35
	s_cselect_b32 s34, s73, s34
	s_cselect_b32 s37, s21, s37
	s_cselect_b32 s36, s72, s36
	s_cselect_b32 s39, s23, s39
	s_cselect_b32 s38, s71, s38
	v_lshl_add_u64 v[194:195], v[144:145], 0, s[30:31]
	s_add_i32 m0, s45, 0xc000
	ds_read_b128 v[182:185], v153
	ds_read_b128 v[186:189], v153 offset:1024
	ds_read_b128 v[190:193], v153 offset:2048
	ds_read_b128 v[202:205], v153 offset:3072
	ds_read_b128 v[206:209], v153 offset:4096
	ds_read_b128 v[210:213], v153 offset:5120
	ds_read_b128 v[214:217], v153 offset:6144
	ds_read_b128 v[218:221], v153 offset:7168
	global_load_lds_dwordx4 v[194:195], off
	v_lshl_add_u64 v[194:195], v[146:147], 0, s[30:31]
	s_add_i32 m0, s45, 0xe000
	s_nop 0
	global_load_lds_dwordx4 v[194:195], off
	s_waitcnt vmcnt(8)
	s_waitcnt lgkmcnt(0)
	s_setprio 1
	s_barrier
	v_mfma_f32_16x16x32_bf16 v[126:129], v[148:151], v[182:185], v[126:129]
	v_mfma_f32_16x16x32_bf16 v[122:125], v[158:161], v[182:185], v[122:125]
	v_mfma_f32_16x16x32_bf16 v[110:113], v[148:151], v[190:193], v[110:113]
	v_mfma_f32_16x16x32_bf16 v[106:109], v[158:161], v[190:193], v[106:109]
	v_mfma_f32_16x16x32_bf16 v[94:97], v[148:151], v[206:209], v[94:97]
	v_mfma_f32_16x16x32_bf16 v[90:93], v[158:161], v[206:209], v[90:93]
	v_mfma_f32_16x16x32_bf16 v[78:81], v[148:151], v[214:217], v[78:81]
	v_mfma_f32_16x16x32_bf16 v[74:77], v[158:161], v[214:217], v[74:77]
	v_mfma_f32_16x16x32_bf16 v[126:129], v[154:157], v[186:189], v[126:129]
	v_mfma_f32_16x16x32_bf16 v[122:125], v[162:165], v[186:189], v[122:125]
	v_mfma_f32_16x16x32_bf16 v[110:113], v[154:157], v[202:205], v[110:113]
	v_mfma_f32_16x16x32_bf16 v[106:109], v[162:165], v[202:205], v[106:109]
	v_mfma_f32_16x16x32_bf16 v[94:97], v[154:157], v[210:213], v[94:97]
	v_mfma_f32_16x16x32_bf16 v[90:93], v[162:165], v[210:213], v[90:93]
	v_mfma_f32_16x16x32_bf16 v[78:81], v[154:157], v[218:221], v[78:81]
	v_mfma_f32_16x16x32_bf16 v[74:77], v[162:165], v[218:221], v[74:77]
	v_mfma_f32_16x16x32_bf16 v[118:121], v[166:169], v[182:185], v[118:121]
	v_mfma_f32_16x16x32_bf16 v[114:117], v[174:177], v[182:185], v[114:117]
	v_mfma_f32_16x16x32_bf16 v[102:105], v[166:169], v[190:193], v[102:105]
	v_mfma_f32_16x16x32_bf16 v[98:101], v[174:177], v[190:193], v[98:101]
	v_mfma_f32_16x16x32_bf16 v[86:89], v[166:169], v[206:209], v[86:89]
	v_mfma_f32_16x16x32_bf16 v[82:85], v[174:177], v[206:209], v[82:85]
	v_mfma_f32_16x16x32_bf16 v[70:73], v[166:169], v[214:217], v[70:73]
	v_mfma_f32_16x16x32_bf16 v[66:69], v[174:177], v[214:217], v[66:69]
	v_mfma_f32_16x16x32_bf16 v[118:121], v[170:173], v[186:189], v[118:121]
	v_mfma_f32_16x16x32_bf16 v[114:117], v[178:181], v[186:189], v[114:117]
	v_mfma_f32_16x16x32_bf16 v[102:105], v[170:173], v[202:205], v[102:105]
	v_mfma_f32_16x16x32_bf16 v[98:101], v[178:181], v[202:205], v[98:101]
	v_mfma_f32_16x16x32_bf16 v[86:89], v[170:173], v[210:213], v[86:89]
	v_mfma_f32_16x16x32_bf16 v[82:85], v[178:181], v[210:213], v[82:85]
	v_mfma_f32_16x16x32_bf16 v[70:73], v[170:173], v[218:221], v[70:73]
	v_mfma_f32_16x16x32_bf16 v[66:69], v[178:181], v[218:221], v[66:69]
	s_barrier
	s_setprio 0
	s_add_i32 s85, s85, s44
	v_lshl_add_u64 v[194:195], s[36:37], 0, v[134:135]
	s_mov_b32 m0, s85
	ds_read_b128 v[182:185], v153 offset:16384
	ds_read_b128 v[186:189], v153 offset:17408
	ds_read_b128 v[190:193], v153 offset:18432
	ds_read_b128 v[202:205], v153 offset:19456
	ds_read_b128 v[206:209], v153 offset:20480
	ds_read_b128 v[210:213], v153 offset:21504
	ds_read_b128 v[214:217], v153 offset:22528
	ds_read_b128 v[218:221], v153 offset:23552
	global_load_lds_dwordx4 v[194:195], off
	s_add_i32 m0, s85, 0x2000
	s_add_u32 s86, s36, 0x40000
	v_lshl_add_u64 v[198:199], s[36:37], 0, v[130:131]
	s_addc_u32 s87, s37, 0
	s_add_i32 s85, vcc_lo, s44
	global_load_lds_dwordx4 v[198:199], off
	v_lshl_add_u64 v[222:223], s[86:87], 0, v[134:135]
	s_mov_b32 m0, s85
	s_nop 0
	global_load_lds_dwordx4 v[222:223], off
	v_lshl_add_u64 v[222:223], s[86:87], 0, v[130:131]
	s_add_i32 m0, s85, 0x2000
	s_nop 0
	global_load_lds_dwordx4 v[222:223], off
	v_lshl_add_u64 v[222:223], s[38:39], 0, v[136:137]
	s_mov_b32 m0, s45
	s_nop 0
	global_load_lds_dwordx4 v[222:223], off
	v_lshl_add_u64 v[222:223], s[38:39], 0, v[132:133]
	s_mov_b32 m0, s51
	s_nop 0
	global_load_lds_dwordx4 v[222:223], off
	s_waitcnt vmcnt(8)
	s_waitcnt lgkmcnt(0)
	s_setprio 1
	s_barrier
	v_mfma_f32_16x16x32_bf16 v[62:65], v[148:151], v[182:185], v[62:65]
	v_mfma_f32_16x16x32_bf16 v[58:61], v[158:161], v[182:185], v[58:61]
	v_mfma_f32_16x16x32_bf16 v[46:49], v[148:151], v[190:193], v[46:49]
	v_mfma_f32_16x16x32_bf16 v[42:45], v[158:161], v[190:193], v[42:45]
	v_mfma_f32_16x16x32_bf16 v[30:33], v[148:151], v[206:209], v[30:33]
	v_mfma_f32_16x16x32_bf16 v[26:29], v[158:161], v[206:209], v[26:29]
	v_mfma_f32_16x16x32_bf16 v[14:17], v[148:151], v[214:217], v[14:17]
	v_mfma_f32_16x16x32_bf16 v[10:13], v[158:161], v[214:217], v[10:13]
	v_mfma_f32_16x16x32_bf16 v[62:65], v[154:157], v[186:189], v[62:65]
	v_mfma_f32_16x16x32_bf16 v[58:61], v[162:165], v[186:189], v[58:61]
	v_mfma_f32_16x16x32_bf16 v[46:49], v[154:157], v[202:205], v[46:49]
	v_mfma_f32_16x16x32_bf16 v[42:45], v[162:165], v[202:205], v[42:45]
	v_mfma_f32_16x16x32_bf16 v[30:33], v[154:157], v[210:213], v[30:33]
	v_mfma_f32_16x16x32_bf16 v[26:29], v[162:165], v[210:213], v[26:29]
	v_mfma_f32_16x16x32_bf16 v[14:17], v[154:157], v[218:221], v[14:17]
	v_mfma_f32_16x16x32_bf16 v[10:13], v[162:165], v[218:221], v[10:13]
	v_mfma_f32_16x16x32_bf16 v[54:57], v[166:169], v[182:185], v[54:57]
	v_mfma_f32_16x16x32_bf16 v[50:53], v[174:177], v[182:185], v[50:53]
	v_mfma_f32_16x16x32_bf16 v[38:41], v[166:169], v[190:193], v[38:41]
	v_mfma_f32_16x16x32_bf16 v[34:37], v[174:177], v[190:193], v[34:37]
	v_mfma_f32_16x16x32_bf16 v[22:25], v[166:169], v[206:209], v[22:25]
	v_mfma_f32_16x16x32_bf16 v[18:21], v[174:177], v[206:209], v[18:21]
	v_mfma_f32_16x16x32_bf16 v[6:9], v[166:169], v[214:217], v[6:9]
	v_mfma_f32_16x16x32_bf16 v[2:5], v[174:177], v[214:217], v[2:5]
	v_mfma_f32_16x16x32_bf16 v[54:57], v[170:173], v[186:189], v[54:57]
	v_mfma_f32_16x16x32_bf16 v[50:53], v[178:181], v[186:189], v[50:53]
	v_mfma_f32_16x16x32_bf16 v[38:41], v[170:173], v[202:205], v[38:41]
	v_mfma_f32_16x16x32_bf16 v[34:37], v[178:181], v[202:205], v[34:37]
	v_mfma_f32_16x16x32_bf16 v[22:25], v[170:173], v[210:213], v[22:25]
	v_mfma_f32_16x16x32_bf16 v[18:21], v[178:181], v[210:213], v[18:21]
	v_mfma_f32_16x16x32_bf16 v[6:9], v[170:173], v[218:221], v[6:9]
	v_mfma_f32_16x16x32_bf16 v[2:5], v[178:181], v[218:221], v[2:5]
	s_barrier
	s_setprio 0
	s_add_i32 s85, 0, 0x18000
	v_add_u32_e32 v0, s85, v152
	s_add_i32 s86, 0, 0x1c000
	ds_read_b128 v[148:151], v0
	ds_read_b128 v[154:157], v0 offset:1024
	ds_read_b128 v[158:161], v0 offset:2048
	ds_read_b128 v[162:165], v0 offset:3072
	v_add_u32_e32 v0, s86, v152
	ds_read_b128 v[166:169], v0
	ds_read_b128 v[170:173], v0 offset:1024
	ds_read_b128 v[174:177], v0 offset:2048
	ds_read_b128 v[178:181], v0 offset:3072
	s_add_u32 s38, s38, 0x40000
	s_addc_u32 s39, s39, 0
	s_mov_b32 m0, s55
	v_lshl_add_u64 v[222:223], s[38:39], 0, v[136:137]
	ds_read_b128 v[182:185], v153 offset:32768
	ds_read_b128 v[186:189], v153 offset:33792
	ds_read_b128 v[190:193], v153 offset:34816
	ds_read_b128 v[202:205], v153 offset:35840
	ds_read_b128 v[206:209], v153 offset:36864
	ds_read_b128 v[210:213], v153 offset:37888
	ds_read_b128 v[214:217], v153 offset:38912
	ds_read_b128 v[218:221], v153 offset:39936
	global_load_lds_dwordx4 v[222:223], off
	v_lshl_add_u64 v[222:223], s[38:39], 0, v[132:133]
	s_mov_b32 m0, s56
	s_nop 0
	global_load_lds_dwordx4 v[222:223], off
	s_waitcnt vmcnt(8)
	s_waitcnt lgkmcnt(0)
	s_setprio 1
	s_barrier
	v_mfma_f32_16x16x32_bf16 v[126:129], v[148:151], v[182:185], v[126:129]
	v_mfma_f32_16x16x32_bf16 v[122:125], v[158:161], v[182:185], v[122:125]
	v_mfma_f32_16x16x32_bf16 v[110:113], v[148:151], v[190:193], v[110:113]
	v_mfma_f32_16x16x32_bf16 v[106:109], v[158:161], v[190:193], v[106:109]
	v_mfma_f32_16x16x32_bf16 v[94:97], v[148:151], v[206:209], v[94:97]
	v_mfma_f32_16x16x32_bf16 v[90:93], v[158:161], v[206:209], v[90:93]
	v_mfma_f32_16x16x32_bf16 v[78:81], v[148:151], v[214:217], v[78:81]
	v_mfma_f32_16x16x32_bf16 v[74:77], v[158:161], v[214:217], v[74:77]
	v_mfma_f32_16x16x32_bf16 v[126:129], v[154:157], v[186:189], v[126:129]
	v_mfma_f32_16x16x32_bf16 v[122:125], v[162:165], v[186:189], v[122:125]
	v_mfma_f32_16x16x32_bf16 v[110:113], v[154:157], v[202:205], v[110:113]
	v_mfma_f32_16x16x32_bf16 v[106:109], v[162:165], v[202:205], v[106:109]
	v_mfma_f32_16x16x32_bf16 v[94:97], v[154:157], v[210:213], v[94:97]
	v_mfma_f32_16x16x32_bf16 v[90:93], v[162:165], v[210:213], v[90:93]
	v_mfma_f32_16x16x32_bf16 v[78:81], v[154:157], v[218:221], v[78:81]
	v_mfma_f32_16x16x32_bf16 v[74:77], v[162:165], v[218:221], v[74:77]
	v_mfma_f32_16x16x32_bf16 v[118:121], v[166:169], v[182:185], v[118:121]
	v_mfma_f32_16x16x32_bf16 v[114:117], v[174:177], v[182:185], v[114:117]
	v_mfma_f32_16x16x32_bf16 v[102:105], v[166:169], v[190:193], v[102:105]
	v_mfma_f32_16x16x32_bf16 v[98:101], v[174:177], v[190:193], v[98:101]
	v_mfma_f32_16x16x32_bf16 v[86:89], v[166:169], v[206:209], v[86:89]
	v_mfma_f32_16x16x32_bf16 v[82:85], v[174:177], v[206:209], v[82:85]
	v_mfma_f32_16x16x32_bf16 v[70:73], v[166:169], v[214:217], v[70:73]
	v_mfma_f32_16x16x32_bf16 v[66:69], v[174:177], v[214:217], v[66:69]
	v_mfma_f32_16x16x32_bf16 v[118:121], v[170:173], v[186:189], v[118:121]
	v_mfma_f32_16x16x32_bf16 v[114:117], v[178:181], v[186:189], v[114:117]
	v_mfma_f32_16x16x32_bf16 v[102:105], v[170:173], v[202:205], v[102:105]
	v_mfma_f32_16x16x32_bf16 v[98:101], v[178:181], v[202:205], v[98:101]
	v_mfma_f32_16x16x32_bf16 v[86:89], v[170:173], v[210:213], v[86:89]
	v_mfma_f32_16x16x32_bf16 v[82:85], v[178:181], v[210:213], v[82:85]
	v_mfma_f32_16x16x32_bf16 v[70:73], v[170:173], v[218:221], v[70:73]
	v_mfma_f32_16x16x32_bf16 v[66:69], v[178:181], v[218:221], v[66:69]
	s_barrier
	s_setprio 0
	s_add_i32 s38, s85, s44
	v_lshl_add_u64 v[194:195], v[194:195], 0, s[90:91]
	s_mov_b32 m0, s38
	ds_read_b128 v[182:185], v153 offset:49152
	ds_read_b128 v[186:189], v153 offset:50176
	ds_read_b128 v[190:193], v153 offset:51200
	ds_read_b128 v[202:205], v153 offset:52224
	ds_read_b128 v[206:209], v153 offset:53248
	ds_read_b128 v[210:213], v153 offset:54272
	ds_read_b128 v[214:217], v153 offset:55296
	ds_read_b128 v[218:221], v153 offset:56320
	global_load_lds_dwordx4 v[194:195], off
	s_add_i32 m0, s38, 0x2000
	s_add_u32 s36, s36, 0x40080
	v_lshl_add_u64 v[194:195], v[198:199], 0, s[90:91]
	s_addc_u32 s37, s37, 0
	s_add_i32 s38, s86, s44
	global_load_lds_dwordx4 v[194:195], off
	v_lshl_add_u64 v[194:195], s[36:37], 0, v[134:135]
	s_mov_b32 m0, s38
	s_nop 0
	global_load_lds_dwordx4 v[194:195], off
	v_lshl_add_u64 v[194:195], s[36:37], 0, v[130:131]
	s_add_i32 m0, s38, 0x2000
	s_nop 0
	global_load_lds_dwordx4 v[194:195], off
	v_lshl_add_u64 v[194:195], s[34:35], 0, v[136:137]
	s_mov_b32 m0, s58
	s_nop 0
	global_load_lds_dwordx4 v[194:195], off
	v_lshl_add_u64 v[194:195], s[34:35], 0, v[132:133]
	s_mov_b32 m0, s59
	s_nop 0
	global_load_lds_dwordx4 v[194:195], off
	s_waitcnt vmcnt(8)
	s_waitcnt lgkmcnt(0)
	s_setprio 1
	s_barrier
	v_mfma_f32_16x16x32_bf16 v[62:65], v[148:151], v[182:185], v[62:65]
	v_mfma_f32_16x16x32_bf16 v[58:61], v[158:161], v[182:185], v[58:61]
	v_mfma_f32_16x16x32_bf16 v[46:49], v[148:151], v[190:193], v[46:49]
	v_mfma_f32_16x16x32_bf16 v[42:45], v[158:161], v[190:193], v[42:45]
	v_mfma_f32_16x16x32_bf16 v[30:33], v[148:151], v[206:209], v[30:33]
	v_mfma_f32_16x16x32_bf16 v[26:29], v[158:161], v[206:209], v[26:29]
	v_mfma_f32_16x16x32_bf16 v[14:17], v[148:151], v[214:217], v[14:17]
	v_mfma_f32_16x16x32_bf16 v[10:13], v[158:161], v[214:217], v[10:13]
	v_mfma_f32_16x16x32_bf16 v[62:65], v[154:157], v[186:189], v[62:65]
	v_mfma_f32_16x16x32_bf16 v[58:61], v[162:165], v[186:189], v[58:61]
	v_mfma_f32_16x16x32_bf16 v[46:49], v[154:157], v[202:205], v[46:49]
	v_mfma_f32_16x16x32_bf16 v[42:45], v[162:165], v[202:205], v[42:45]
	v_mfma_f32_16x16x32_bf16 v[30:33], v[154:157], v[210:213], v[30:33]
	v_mfma_f32_16x16x32_bf16 v[26:29], v[162:165], v[210:213], v[26:29]
	v_mfma_f32_16x16x32_bf16 v[14:17], v[154:157], v[218:221], v[14:17]
	v_mfma_f32_16x16x32_bf16 v[10:13], v[162:165], v[218:221], v[10:13]
	v_mfma_f32_16x16x32_bf16 v[54:57], v[166:169], v[182:185], v[54:57]
	v_mfma_f32_16x16x32_bf16 v[50:53], v[174:177], v[182:185], v[50:53]
	v_mfma_f32_16x16x32_bf16 v[38:41], v[166:169], v[190:193], v[38:41]
	v_mfma_f32_16x16x32_bf16 v[34:37], v[174:177], v[190:193], v[34:37]
	v_mfma_f32_16x16x32_bf16 v[22:25], v[166:169], v[206:209], v[22:25]
	v_mfma_f32_16x16x32_bf16 v[18:21], v[174:177], v[206:209], v[18:21]
	v_mfma_f32_16x16x32_bf16 v[6:9], v[166:169], v[214:217], v[6:9]
	v_mfma_f32_16x16x32_bf16 v[2:5], v[174:177], v[214:217], v[2:5]
	v_mfma_f32_16x16x32_bf16 v[54:57], v[170:173], v[186:189], v[54:57]
	v_mfma_f32_16x16x32_bf16 v[50:53], v[178:181], v[186:189], v[50:53]
	v_mfma_f32_16x16x32_bf16 v[38:41], v[170:173], v[202:205], v[38:41]
	v_mfma_f32_16x16x32_bf16 v[34:37], v[178:181], v[202:205], v[34:37]
	v_mfma_f32_16x16x32_bf16 v[22:25], v[170:173], v[210:213], v[22:25]
	v_mfma_f32_16x16x32_bf16 v[18:21], v[178:181], v[210:213], v[18:21]
	v_mfma_f32_16x16x32_bf16 v[6:9], v[170:173], v[218:221], v[6:9]
	v_mfma_f32_16x16x32_bf16 v[2:5], v[178:181], v[218:221], v[2:5]
	s_barrier
	s_setprio 0
	s_add_i32 s78, s78, 2
	s_add_u32 s30, s30, 0x100
	s_addc_u32 s31, s31, 0
	s_cmp_gt_u32 s78, 13
	s_cbranch_scc0 .LBB0_345
	s_and_b64 vcc, exec, s[16:17]
	s_cbranch_vccz .LBB0_348
	s_barrier

.LBB0_541:
	s_add_i32 s78, s78, 2
	s_cmp_gt_u32 s78, 7
	s_cselect_b32 vcc_lo, 0xffffec00, 0
	s_cselect_b32 vcc_hi, -1, 0
	s_cmp_gt_u32 s78, 5
	s_cselect_b32 s11, 0xffffec00, 0
	s_cselect_b32 s10, -1, 0
	s_add_u32 s11, s11, s36
	s_addc_u32 s10, s10, s37
	s_add_u32 s11, s34, s11
	s_addc_u32 s10, s35, s10
	s_add_u32 s11, s11, 0x100
	s_addc_u32 s10, s10, 0
	s_add_u32 s38, s86, s36
	s_addc_u32 s39, s87, s37
	s_cmp_gt_u32 s78, 4
	s_cselect_b32 s41, 0xffffec00, 0
	s_cselect_b32 s40, -1, 0
	s_add_u32 s41, s41, s36
	s_addc_u32 s40, s40, s37
	s_add_u32 s41, s34, s41
	s_addc_u32 s40, s35, s40
	s_add_u32 s4, s41, 0x180
	s_addc_u32 s5, s40, 0
	s_cmpk_eq_i32 s36, 0x700
	s_cselect_b32 s41, s29, s10
	s_cselect_b32 s40, s28, s11
	s_cselect_b32 s39, s73, s39
	s_cselect_b32 s38, s74, s38
	s_cselect_b32 s11, s76, s5
	s_cselect_b32 s10, s75, s4
	s_add_i32 s4, 0, 0x10000
	v_add_u32_e32 v0, s4, v244
	s_add_i32 s5, 0, 0x14000
	ds_read_b128 v[132:135], v0
	ds_read_b128 v[136:139], v0 offset:1024
	ds_read_b128 v[144:147], v0 offset:2048
	ds_read_b128 v[148:151], v0 offset:3072
	v_add_u32_e32 v0, s5, v244
	ds_read_b128 v[152:155], v0
	ds_read_b128 v[156:159], v0 offset:1024
	ds_read_b128 v[160:163], v0 offset:2048
	ds_read_b128 v[164:167], v0 offset:3072
	s_add_u32 vcc_lo, vcc_lo, s36
	s_addc_u32 vcc_hi, vcc_hi, s37
	v_lshl_add_u64 v[2:3], v[140:141], 0, vcc
	s_add_i32 m0, s55, 0xc000
	ds_read_b128 v[168:171], v246
	ds_read_b128 v[172:175], v246 offset:1024
	ds_read_b128 v[176:179], v246 offset:2048
	ds_read_b128 v[180:183], v246 offset:3072
	ds_read_b128 v[184:187], v246 offset:4096
	ds_read_b128 v[188:191], v246 offset:5120
	ds_read_b128 v[212:215], v246 offset:6144
	ds_read_b128 v[216:219], v246 offset:7168
	global_load_lds_dwordx4 v[2:3], off
	v_lshl_add_u64 v[2:3], v[142:143], 0, vcc
	s_add_i32 m0, s55, 0xe000
	s_nop 0
	global_load_lds_dwordx4 v[2:3], off
	s_waitcnt vmcnt(8)
	s_waitcnt lgkmcnt(0)
	s_setprio 1
	s_barrier
	v_mfma_f32_16x16x32_bf16 v[128:131], v[132:135], v[168:171], v[128:131]
	v_mfma_f32_16x16x32_bf16 v[124:127], v[144:147], v[168:171], v[124:127]
	v_mfma_f32_16x16x32_bf16 v[112:115], v[132:135], v[176:179], v[112:115]
	v_mfma_f32_16x16x32_bf16 v[108:111], v[144:147], v[176:179], v[108:111]
	v_mfma_f32_16x16x32_bf16 v[96:99], v[132:135], v[184:187], v[96:99]
	v_mfma_f32_16x16x32_bf16 v[92:95], v[144:147], v[184:187], v[92:95]
	v_mfma_f32_16x16x32_bf16 v[80:83], v[132:135], v[212:215], v[80:83]
	v_mfma_f32_16x16x32_bf16 v[76:79], v[144:147], v[212:215], v[76:79]
	v_mfma_f32_16x16x32_bf16 v[128:131], v[136:139], v[172:175], v[128:131]
	v_mfma_f32_16x16x32_bf16 v[124:127], v[148:151], v[172:175], v[124:127]
	v_mfma_f32_16x16x32_bf16 v[112:115], v[136:139], v[180:183], v[112:115]
	v_mfma_f32_16x16x32_bf16 v[108:111], v[148:151], v[180:183], v[108:111]
	v_mfma_f32_16x16x32_bf16 v[96:99], v[136:139], v[188:191], v[96:99]
	v_mfma_f32_16x16x32_bf16 v[92:95], v[148:151], v[188:191], v[92:95]
	v_mfma_f32_16x16x32_bf16 v[80:83], v[136:139], v[216:219], v[80:83]
	v_mfma_f32_16x16x32_bf16 v[76:79], v[148:151], v[216:219], v[76:79]
	v_mfma_f32_16x16x32_bf16 v[120:123], v[152:155], v[168:171], v[120:123]
	v_mfma_f32_16x16x32_bf16 v[116:119], v[160:163], v[168:171], v[116:119]
	v_mfma_f32_16x16x32_bf16 v[104:107], v[152:155], v[176:179], v[104:107]
	v_mfma_f32_16x16x32_bf16 v[100:103], v[160:163], v[176:179], v[100:103]
	v_mfma_f32_16x16x32_bf16 v[88:91], v[152:155], v[184:187], v[88:91]
	v_mfma_f32_16x16x32_bf16 v[84:87], v[160:163], v[184:187], v[84:87]
	v_mfma_f32_16x16x32_bf16 v[72:75], v[152:155], v[212:215], v[72:75]
	v_mfma_f32_16x16x32_bf16 v[68:71], v[160:163], v[212:215], v[68:71]
	v_mfma_f32_16x16x32_bf16 v[120:123], v[156:159], v[172:175], v[120:123]
	v_mfma_f32_16x16x32_bf16 v[116:119], v[164:167], v[172:175], v[116:119]
	v_mfma_f32_16x16x32_bf16 v[104:107], v[156:159], v[180:183], v[104:107]
	v_mfma_f32_16x16x32_bf16 v[100:103], v[164:167], v[180:183], v[100:103]
	v_mfma_f32_16x16x32_bf16 v[88:91], v[156:159], v[188:191], v[88:91]
	v_mfma_f32_16x16x32_bf16 v[84:87], v[164:167], v[188:191], v[84:87]
	v_mfma_f32_16x16x32_bf16 v[72:75], v[156:159], v[216:219], v[72:75]
	v_mfma_f32_16x16x32_bf16 v[68:71], v[164:167], v[216:219], v[68:71]
	s_barrier
	s_setprio 0
	s_add_i32 s4, s4, s51
	v_lshl_add_u64 v[194:195], s[38:39], 0, v[204:205]
	s_mov_b32 m0, s4
	ds_read_b128 v[168:171], v246 offset:16384
	ds_read_b128 v[172:175], v246 offset:17408
	ds_read_b128 v[176:179], v246 offset:18432
	ds_read_b128 v[180:183], v246 offset:19456
	ds_read_b128 v[184:187], v246 offset:20480
	ds_read_b128 v[188:191], v246 offset:21504
	ds_read_b128 v[212:215], v246 offset:22528
	ds_read_b128 v[216:219], v246 offset:23552
	global_load_lds_dwordx4 v[194:195], off
	s_add_i32 m0, s4, 0x2000
	s_add_u32 vcc_lo, s38, 0x40000
	v_lshl_add_u64 v[198:199], s[38:39], 0, v[192:193]
	s_addc_u32 vcc_hi, s39, 0
	s_add_i32 s4, s5, s51
	global_load_lds_dwordx4 v[198:199], off
	v_lshl_add_u64 v[2:3], vcc, 0, v[204:205]
	s_mov_b32 m0, s4
	s_nop 0
	global_load_lds_dwordx4 v[2:3], off
	v_lshl_add_u64 v[2:3], vcc, 0, v[192:193]
	s_add_i32 m0, s4, 0x2000
	s_nop 0
	global_load_lds_dwordx4 v[2:3], off
	v_lshl_add_u64 v[2:3], s[40:41], 0, v[206:207]
	s_mov_b32 m0, s55
	s_nop 0
	global_load_lds_dwordx4 v[2:3], off
	v_lshl_add_u64 v[2:3], s[40:41], 0, v[202:203]
	s_mov_b32 m0, s56
	s_nop 0
	global_load_lds_dwordx4 v[2:3], off
	s_waitcnt vmcnt(8)
	s_waitcnt lgkmcnt(0)
	s_setprio 1
	s_barrier
	v_mfma_f32_16x16x32_bf16 v[64:67], v[132:135], v[168:171], v[64:67]
	v_mfma_f32_16x16x32_bf16 v[60:63], v[144:147], v[168:171], v[60:63]
	v_mfma_f32_16x16x32_bf16 v[48:51], v[132:135], v[176:179], v[48:51]
	v_mfma_f32_16x16x32_bf16 v[44:47], v[144:147], v[176:179], v[44:47]
	v_mfma_f32_16x16x32_bf16 v[32:35], v[132:135], v[184:187], v[32:35]
	v_mfma_f32_16x16x32_bf16 v[28:31], v[144:147], v[184:187], v[28:31]
	v_mfma_f32_16x16x32_bf16 v[16:19], v[132:135], v[212:215], v[16:19]
	v_mfma_f32_16x16x32_bf16 v[12:15], v[144:147], v[212:215], v[12:15]
	v_mfma_f32_16x16x32_bf16 v[64:67], v[136:139], v[172:175], v[64:67]
	v_mfma_f32_16x16x32_bf16 v[60:63], v[148:151], v[172:175], v[60:63]
	v_mfma_f32_16x16x32_bf16 v[48:51], v[136:139], v[180:183], v[48:51]
	v_mfma_f32_16x16x32_bf16 v[44:47], v[148:151], v[180:183], v[44:47]
	v_mfma_f32_16x16x32_bf16 v[32:35], v[136:139], v[188:191], v[32:35]
	v_mfma_f32_16x16x32_bf16 v[28:31], v[148:151], v[188:191], v[28:31]
	v_mfma_f32_16x16x32_bf16 v[16:19], v[136:139], v[216:219], v[16:19]
	v_mfma_f32_16x16x32_bf16 v[12:15], v[148:151], v[216:219], v[12:15]
	v_mfma_f32_16x16x32_bf16 v[56:59], v[152:155], v[168:171], v[56:59]
	v_mfma_f32_16x16x32_bf16 v[52:55], v[160:163], v[168:171], v[52:55]
	v_mfma_f32_16x16x32_bf16 v[40:43], v[152:155], v[176:179], v[40:43]
	v_mfma_f32_16x16x32_bf16 v[36:39], v[160:163], v[176:179], v[36:39]
	v_mfma_f32_16x16x32_bf16 v[24:27], v[152:155], v[184:187], v[24:27]
	v_mfma_f32_16x16x32_bf16 v[20:23], v[160:163], v[184:187], v[20:23]
	v_mfma_f32_16x16x32_bf16 v[8:11], v[152:155], v[212:215], v[8:11]
	v_mfma_f32_16x16x32_bf16 v[2:5], v[160:163], v[212:215], v[4:7]
	v_mfma_f32_16x16x32_bf16 v[56:59], v[156:159], v[172:175], v[56:59]
	v_mfma_f32_16x16x32_bf16 v[52:55], v[164:167], v[172:175], v[52:55]
	v_mfma_f32_16x16x32_bf16 v[40:43], v[156:159], v[180:183], v[40:43]
	v_mfma_f32_16x16x32_bf16 v[36:39], v[164:167], v[180:183], v[36:39]
	v_mfma_f32_16x16x32_bf16 v[24:27], v[156:159], v[188:191], v[24:27]
	v_mfma_f32_16x16x32_bf16 v[20:23], v[164:167], v[188:191], v[20:23]
	v_mfma_f32_16x16x32_bf16 v[8:11], v[156:159], v[216:219], v[8:11]
	v_mfma_f32_16x16x32_bf16 v[2:5], v[164:167], v[216:219], v[2:5]
	s_barrier
	s_setprio 0
	s_add_i32 s4, 0, 0x18000
	v_add_u32_e32 v0, s4, v244
	s_add_i32 s5, 0, 0x1c000
	ds_read_b128 v[132:135], v0
	ds_read_b128 v[136:139], v0 offset:1024
	ds_read_b128 v[144:147], v0 offset:2048
	ds_read_b128 v[148:151], v0 offset:3072
	v_add_u32_e32 v0, s5, v244
	ds_read_b128 v[152:155], v0
	ds_read_b128 v[156:159], v0 offset:1024
	ds_read_b128 v[160:163], v0 offset:2048
	ds_read_b128 v[164:167], v0 offset:3072
	s_add_u32 s40, s40, 0xe0000
	s_addc_u32 s41, s41, 0
	s_mov_b32 m0, s57
	v_lshl_add_u64 v[6:7], s[40:41], 0, v[206:207]
	ds_read_b128 v[168:171], v246 offset:32768
	ds_read_b128 v[172:175], v246 offset:33792
	ds_read_b128 v[176:179], v246 offset:34816
	ds_read_b128 v[180:183], v246 offset:35840
	ds_read_b128 v[184:187], v246 offset:36864
	ds_read_b128 v[188:191], v246 offset:37888
	ds_read_b128 v[212:215], v246 offset:38912
	ds_read_b128 v[216:219], v246 offset:39936
	global_load_lds_dwordx4 v[6:7], off
	v_lshl_add_u64 v[6:7], s[40:41], 0, v[202:203]
	s_mov_b32 m0, s58
	s_nop 0
	global_load_lds_dwordx4 v[6:7], off
	s_waitcnt vmcnt(8)
	s_waitcnt lgkmcnt(0)
	s_setprio 1
	s_barrier
	v_mfma_f32_16x16x32_bf16 v[128:131], v[132:135], v[168:171], v[128:131]
	v_mfma_f32_16x16x32_bf16 v[124:127], v[144:147], v[168:171], v[124:127]
	v_mfma_f32_16x16x32_bf16 v[112:115], v[132:135], v[176:179], v[112:115]
	v_mfma_f32_16x16x32_bf16 v[108:111], v[144:147], v[176:179], v[108:111]
	v_mfma_f32_16x16x32_bf16 v[96:99], v[132:135], v[184:187], v[96:99]
	v_mfma_f32_16x16x32_bf16 v[92:95], v[144:147], v[184:187], v[92:95]
	v_mfma_f32_16x16x32_bf16 v[80:83], v[132:135], v[212:215], v[80:83]
	v_mfma_f32_16x16x32_bf16 v[76:79], v[144:147], v[212:215], v[76:79]
	v_mfma_f32_16x16x32_bf16 v[128:131], v[136:139], v[172:175], v[128:131]
	v_mfma_f32_16x16x32_bf16 v[124:127], v[148:151], v[172:175], v[124:127]
	v_mfma_f32_16x16x32_bf16 v[112:115], v[136:139], v[180:183], v[112:115]
	v_mfma_f32_16x16x32_bf16 v[108:111], v[148:151], v[180:183], v[108:111]
	v_mfma_f32_16x16x32_bf16 v[96:99], v[136:139], v[188:191], v[96:99]
	v_mfma_f32_16x16x32_bf16 v[92:95], v[148:151], v[188:191], v[92:95]
	v_mfma_f32_16x16x32_bf16 v[80:83], v[136:139], v[216:219], v[80:83]
	v_mfma_f32_16x16x32_bf16 v[76:79], v[148:151], v[216:219], v[76:79]
	v_mfma_f32_16x16x32_bf16 v[120:123], v[152:155], v[168:171], v[120:123]
	v_mfma_f32_16x16x32_bf16 v[116:119], v[160:163], v[168:171], v[116:119]
	v_mfma_f32_16x16x32_bf16 v[104:107], v[152:155], v[176:179], v[104:107]
	v_mfma_f32_16x16x32_bf16 v[100:103], v[160:163], v[176:179], v[100:103]
	v_mfma_f32_16x16x32_bf16 v[88:91], v[152:155], v[184:187], v[88:91]
	v_mfma_f32_16x16x32_bf16 v[84:87], v[160:163], v[184:187], v[84:87]
	v_mfma_f32_16x16x32_bf16 v[72:75], v[152:155], v[212:215], v[72:75]
	v_mfma_f32_16x16x32_bf16 v[68:71], v[160:163], v[212:215], v[68:71]
	v_mfma_f32_16x16x32_bf16 v[120:123], v[156:159], v[172:175], v[120:123]
	v_mfma_f32_16x16x32_bf16 v[116:119], v[164:167], v[172:175], v[116:119]
	v_mfma_f32_16x16x32_bf16 v[104:107], v[156:159], v[180:183], v[104:107]
	v_mfma_f32_16x16x32_bf16 v[100:103], v[164:167], v[180:183], v[100:103]
	v_mfma_f32_16x16x32_bf16 v[88:91], v[156:159], v[188:191], v[88:91]
	v_mfma_f32_16x16x32_bf16 v[84:87], v[164:167], v[188:191], v[84:87]
	v_mfma_f32_16x16x32_bf16 v[72:75], v[156:159], v[216:219], v[72:75]
	v_mfma_f32_16x16x32_bf16 v[68:71], v[164:167], v[216:219], v[68:71]
	s_barrier
	s_setprio 0
	s_add_i32 s4, s4, s51
	v_lshl_add_u64 v[6:7], v[194:195], 0, s[90:91]
	s_mov_b32 m0, s4
	ds_read_b128 v[168:171], v246 offset:49152
	ds_read_b128 v[172:175], v246 offset:50176
	ds_read_b128 v[176:179], v246 offset:51200
	ds_read_b128 v[180:183], v246 offset:52224
	ds_read_b128 v[184:187], v246 offset:53248
	ds_read_b128 v[188:191], v246 offset:54272
	ds_read_b128 v[212:215], v246 offset:55296
	ds_read_b128 v[216:219], v246 offset:56320
	global_load_lds_dwordx4 v[6:7], off
	s_add_i32 m0, s4, 0x2000
	s_add_u32 s38, s38, 0x40080
	v_lshl_add_u64 v[6:7], v[198:199], 0, s[90:91]
	s_addc_u32 s39, s39, 0
	s_add_i32 s4, s5, s51
	global_load_lds_dwordx4 v[6:7], off
	v_lshl_add_u64 v[6:7], s[38:39], 0, v[204:205]
	s_mov_b32 m0, s4
	s_nop 0
	global_load_lds_dwordx4 v[6:7], off
	v_lshl_add_u64 v[6:7], s[38:39], 0, v[192:193]
	s_add_i32 m0, s4, 0x2000
	s_nop 0
	global_load_lds_dwordx4 v[6:7], off
	v_lshl_add_u64 v[6:7], s[10:11], 0, v[206:207]
	s_mov_b32 m0, s68
	s_nop 0
	global_load_lds_dwordx4 v[6:7], off
	v_lshl_add_u64 v[6:7], s[10:11], 0, v[202:203]
	s_mov_b32 m0, s69
	s_nop 0
	global_load_lds_dwordx4 v[6:7], off
	s_waitcnt vmcnt(8)
	s_waitcnt lgkmcnt(0)
	s_setprio 1
	s_barrier
	v_mfma_f32_16x16x32_bf16 v[64:67], v[132:135], v[168:171], v[64:67]
	v_mfma_f32_16x16x32_bf16 v[60:63], v[144:147], v[168:171], v[60:63]
	v_mfma_f32_16x16x32_bf16 v[48:51], v[132:135], v[176:179], v[48:51]
	v_mfma_f32_16x16x32_bf16 v[44:47], v[144:147], v[176:179], v[44:47]
	v_mfma_f32_16x16x32_bf16 v[32:35], v[132:135], v[184:187], v[32:35]
	v_mfma_f32_16x16x32_bf16 v[28:31], v[144:147], v[184:187], v[28:31]
	v_mfma_f32_16x16x32_bf16 v[16:19], v[132:135], v[212:215], v[16:19]
	v_mfma_f32_16x16x32_bf16 v[12:15], v[144:147], v[212:215], v[12:15]
	v_mfma_f32_16x16x32_bf16 v[64:67], v[136:139], v[172:175], v[64:67]
	v_mfma_f32_16x16x32_bf16 v[60:63], v[148:151], v[172:175], v[60:63]
	v_mfma_f32_16x16x32_bf16 v[48:51], v[136:139], v[180:183], v[48:51]
	v_mfma_f32_16x16x32_bf16 v[44:47], v[148:151], v[180:183], v[44:47]
	v_mfma_f32_16x16x32_bf16 v[32:35], v[136:139], v[188:191], v[32:35]
	v_mfma_f32_16x16x32_bf16 v[28:31], v[148:151], v[188:191], v[28:31]
	v_mfma_f32_16x16x32_bf16 v[16:19], v[136:139], v[216:219], v[16:19]
	v_mfma_f32_16x16x32_bf16 v[12:15], v[148:151], v[216:219], v[12:15]
	v_mfma_f32_16x16x32_bf16 v[56:59], v[152:155], v[168:171], v[56:59]
	v_mfma_f32_16x16x32_bf16 v[52:55], v[160:163], v[168:171], v[52:55]
	v_mfma_f32_16x16x32_bf16 v[40:43], v[152:155], v[176:179], v[40:43]
	v_mfma_f32_16x16x32_bf16 v[36:39], v[160:163], v[176:179], v[36:39]
	v_mfma_f32_16x16x32_bf16 v[24:27], v[152:155], v[184:187], v[24:27]
	v_mfma_f32_16x16x32_bf16 v[20:23], v[160:163], v[184:187], v[20:23]
	v_mfma_f32_16x16x32_bf16 v[6:9], v[152:155], v[212:215], v[8:11]
	v_mfma_f32_16x16x32_bf16 v[2:5], v[160:163], v[212:215], v[2:5]
	v_mfma_f32_16x16x32_bf16 v[56:59], v[156:159], v[172:175], v[56:59]
	v_mfma_f32_16x16x32_bf16 v[52:55], v[164:167], v[172:175], v[52:55]
	v_mfma_f32_16x16x32_bf16 v[40:43], v[156:159], v[180:183], v[40:43]
	v_mfma_f32_16x16x32_bf16 v[36:39], v[164:167], v[180:183], v[36:39]
	v_mfma_f32_16x16x32_bf16 v[24:27], v[156:159], v[188:191], v[24:27]
	v_mfma_f32_16x16x32_bf16 v[20:23], v[164:167], v[188:191], v[20:23]
	v_mfma_f32_16x16x32_bf16 v[8:11], v[156:159], v[216:219], v[6:9]
	v_mfma_f32_16x16x32_bf16 v[4:7], v[164:167], v[216:219], v[2:5]
	s_barrier
	s_setprio 0
	s_add_u32 s36, s36, 0x100
	s_addc_u32 s37, s37, 0
	s_cmp_gt_u32 s78, 13
	s_cbranch_scc1 .LBB0_544

.LBB0_585:
	s_add_i32 s78, s78, 2
	s_cmp_gt_u32 s78, 7
	s_cselect_b32 s85, 0xffffec00, 0
	s_cselect_b32 s87, -1, 0
	s_cmp_gt_u32 s78, 5
	s_cselect_b32 s35, 0xffffec00, 0
	s_cselect_b32 s34, -1, 0
	s_add_u32 s35, s35, s12
	s_addc_u32 s34, s34, s13
	s_add_u32 s35, s30, s35
	s_addc_u32 s34, s31, s34
	s_add_u32 s35, s35, 0x100
	s_addc_u32 s34, s34, 0
	s_add_u32 s36, s75, s12
	s_addc_u32 s37, s76, s13
	s_cmp_gt_u32 s78, 4
	s_cselect_b32 s39, 0xffffec00, 0
	s_cselect_b32 s38, -1, 0
	s_add_u32 s39, s39, s12
	s_addc_u32 s38, s38, s13
	s_add_u32 s39, s30, s39
	s_addc_u32 s38, s31, s38
	s_add_u32 s86, s39, 0x180
	s_addc_u32 vcc_lo, s38, 0
	s_cmpk_eq_i32 s12, 0x700
	s_cselect_b32 s39, s27, s34
	s_cselect_b32 s38, s26, s35
	s_cselect_b32 s37, s25, s37
	s_cselect_b32 s36, s72, s36
	s_cselect_b32 s35, s74, vcc_lo
	s_cselect_b32 s34, s73, s86
	s_add_i32 vcc_lo, 0, 0x10000
	v_add_u32_e32 v0, vcc_lo, v243
	s_add_i32 vcc_hi, 0, 0x14000
	ds_read_b128 v[128:131], v0
	ds_read_b128 v[132:135], v0 offset:1024
	ds_read_b128 v[136:139], v0 offset:2048
	ds_read_b128 v[140:143], v0 offset:3072
	v_add_u32_e32 v0, vcc_hi, v243
	ds_read_b128 v[152:155], v0
	ds_read_b128 v[156:159], v0 offset:1024
	ds_read_b128 v[160:163], v0 offset:2048
	ds_read_b128 v[164:167], v0 offset:3072
	s_add_u32 s86, s85, s12
	s_addc_u32 s87, s87, s13
	v_lshl_add_u64 v[2:3], v[124:125], 0, s[86:87]
	s_add_i32 m0, s41, 0xc000
	ds_read_b128 v[168:171], v245
	ds_read_b128 v[172:175], v245 offset:1024
	ds_read_b128 v[176:179], v245 offset:2048
	ds_read_b128 v[180:183], v245 offset:3072
	ds_read_b128 v[184:187], v245 offset:4096
	ds_read_b128 v[188:191], v245 offset:5120
	ds_read_b128 v[212:215], v245 offset:6144
	ds_read_b128 v[216:219], v245 offset:7168
	global_load_lds_dwordx4 v[2:3], off
	v_lshl_add_u64 v[2:3], v[126:127], 0, s[86:87]
	s_add_i32 m0, s41, 0xe000
	s_nop 0
	global_load_lds_dwordx4 v[2:3], off
	s_waitcnt vmcnt(8)
	s_waitcnt lgkmcnt(0)
	s_setprio 1
	s_barrier
	v_mfma_f32_16x16x32_bf16 v[148:151], v[128:131], v[168:171], v[148:151]
	v_mfma_f32_16x16x32_bf16 v[144:147], v[136:139], v[168:171], v[144:147]
	v_mfma_f32_16x16x32_bf16 v[112:115], v[128:131], v[176:179], v[112:115]
	v_mfma_f32_16x16x32_bf16 v[108:111], v[136:139], v[176:179], v[108:111]
	v_mfma_f32_16x16x32_bf16 v[96:99], v[128:131], v[184:187], v[96:99]
	v_mfma_f32_16x16x32_bf16 v[92:95], v[136:139], v[184:187], v[92:95]
	v_mfma_f32_16x16x32_bf16 v[80:83], v[128:131], v[212:215], v[80:83]
	v_mfma_f32_16x16x32_bf16 v[76:79], v[136:139], v[212:215], v[76:79]
	v_mfma_f32_16x16x32_bf16 v[148:151], v[132:135], v[172:175], v[148:151]
	v_mfma_f32_16x16x32_bf16 v[144:147], v[140:143], v[172:175], v[144:147]
	v_mfma_f32_16x16x32_bf16 v[112:115], v[132:135], v[180:183], v[112:115]
	v_mfma_f32_16x16x32_bf16 v[108:111], v[140:143], v[180:183], v[108:111]
	v_mfma_f32_16x16x32_bf16 v[96:99], v[132:135], v[188:191], v[96:99]
	v_mfma_f32_16x16x32_bf16 v[92:95], v[140:143], v[188:191], v[92:95]
	v_mfma_f32_16x16x32_bf16 v[80:83], v[132:135], v[216:219], v[80:83]
	v_mfma_f32_16x16x32_bf16 v[76:79], v[140:143], v[216:219], v[76:79]
	v_mfma_f32_16x16x32_bf16 v[120:123], v[152:155], v[168:171], v[120:123]
	v_mfma_f32_16x16x32_bf16 v[116:119], v[160:163], v[168:171], v[116:119]
	v_mfma_f32_16x16x32_bf16 v[104:107], v[152:155], v[176:179], v[104:107]
	v_mfma_f32_16x16x32_bf16 v[100:103], v[160:163], v[176:179], v[100:103]
	v_mfma_f32_16x16x32_bf16 v[88:91], v[152:155], v[184:187], v[88:91]
	v_mfma_f32_16x16x32_bf16 v[84:87], v[160:163], v[184:187], v[84:87]
	v_mfma_f32_16x16x32_bf16 v[72:75], v[152:155], v[212:215], v[72:75]
	v_mfma_f32_16x16x32_bf16 v[68:71], v[160:163], v[212:215], v[68:71]
	v_mfma_f32_16x16x32_bf16 v[120:123], v[156:159], v[172:175], v[120:123]
	v_mfma_f32_16x16x32_bf16 v[116:119], v[164:167], v[172:175], v[116:119]
	v_mfma_f32_16x16x32_bf16 v[104:107], v[156:159], v[180:183], v[104:107]
	v_mfma_f32_16x16x32_bf16 v[100:103], v[164:167], v[180:183], v[100:103]
	v_mfma_f32_16x16x32_bf16 v[88:91], v[156:159], v[188:191], v[88:91]
	v_mfma_f32_16x16x32_bf16 v[84:87], v[164:167], v[188:191], v[84:87]
	v_mfma_f32_16x16x32_bf16 v[72:75], v[156:159], v[216:219], v[72:75]
	v_mfma_f32_16x16x32_bf16 v[68:71], v[164:167], v[216:219], v[68:71]
	s_barrier
	s_setprio 0
	s_add_i32 s85, vcc_lo, s40
	v_lshl_add_u64 v[194:195], s[36:37], 0, v[204:205]
	s_mov_b32 m0, s85
	ds_read_b128 v[168:171], v245 offset:16384
	ds_read_b128 v[172:175], v245 offset:17408
	ds_read_b128 v[176:179], v245 offset:18432
	ds_read_b128 v[180:183], v245 offset:19456
	ds_read_b128 v[184:187], v245 offset:20480
	ds_read_b128 v[188:191], v245 offset:21504
	ds_read_b128 v[212:215], v245 offset:22528
	ds_read_b128 v[216:219], v245 offset:23552
	global_load_lds_dwordx4 v[194:195], off
	s_add_i32 m0, s85, 0x2000
	s_add_u32 s86, s36, 0x40000
	v_lshl_add_u64 v[198:199], s[36:37], 0, v[192:193]
	s_addc_u32 s87, s37, 0
	s_add_i32 s85, vcc_hi, s40
	global_load_lds_dwordx4 v[198:199], off
	v_lshl_add_u64 v[2:3], s[86:87], 0, v[204:205]
	s_mov_b32 m0, s85
	s_nop 0
	global_load_lds_dwordx4 v[2:3], off
	v_lshl_add_u64 v[2:3], s[86:87], 0, v[192:193]
	s_add_i32 m0, s85, 0x2000
	s_nop 0
	global_load_lds_dwordx4 v[2:3], off
	v_lshl_add_u64 v[2:3], s[38:39], 0, v[206:207]
	s_mov_b32 m0, s41
	s_nop 0
	global_load_lds_dwordx4 v[2:3], off
	v_lshl_add_u64 v[2:3], s[38:39], 0, v[202:203]
	s_mov_b32 m0, s51
	s_nop 0
	global_load_lds_dwordx4 v[2:3], off
	s_waitcnt vmcnt(8)
	s_waitcnt lgkmcnt(0)
	s_setprio 1
	s_barrier
	v_mfma_f32_16x16x32_bf16 v[64:67], v[128:131], v[168:171], v[64:67]
	v_mfma_f32_16x16x32_bf16 v[60:63], v[136:139], v[168:171], v[60:63]
	v_mfma_f32_16x16x32_bf16 v[48:51], v[128:131], v[176:179], v[48:51]
	v_mfma_f32_16x16x32_bf16 v[44:47], v[136:139], v[176:179], v[44:47]
	v_mfma_f32_16x16x32_bf16 v[32:35], v[128:131], v[184:187], v[32:35]
	v_mfma_f32_16x16x32_bf16 v[28:31], v[136:139], v[184:187], v[28:31]
	v_mfma_f32_16x16x32_bf16 v[16:19], v[128:131], v[212:215], v[16:19]
	v_mfma_f32_16x16x32_bf16 v[12:15], v[136:139], v[212:215], v[12:15]
	v_mfma_f32_16x16x32_bf16 v[64:67], v[132:135], v[172:175], v[64:67]
	v_mfma_f32_16x16x32_bf16 v[60:63], v[140:143], v[172:175], v[60:63]
	v_mfma_f32_16x16x32_bf16 v[48:51], v[132:135], v[180:183], v[48:51]
	v_mfma_f32_16x16x32_bf16 v[44:47], v[140:143], v[180:183], v[44:47]
	v_mfma_f32_16x16x32_bf16 v[32:35], v[132:135], v[188:191], v[32:35]
	v_mfma_f32_16x16x32_bf16 v[28:31], v[140:143], v[188:191], v[28:31]
	v_mfma_f32_16x16x32_bf16 v[16:19], v[132:135], v[216:219], v[16:19]
	v_mfma_f32_16x16x32_bf16 v[12:15], v[140:143], v[216:219], v[12:15]
	v_mfma_f32_16x16x32_bf16 v[56:59], v[152:155], v[168:171], v[56:59]
	v_mfma_f32_16x16x32_bf16 v[52:55], v[160:163], v[168:171], v[52:55]
	v_mfma_f32_16x16x32_bf16 v[40:43], v[152:155], v[176:179], v[40:43]
	v_mfma_f32_16x16x32_bf16 v[36:39], v[160:163], v[176:179], v[36:39]
	v_mfma_f32_16x16x32_bf16 v[24:27], v[152:155], v[184:187], v[24:27]
	v_mfma_f32_16x16x32_bf16 v[20:23], v[160:163], v[184:187], v[20:23]
	v_mfma_f32_16x16x32_bf16 v[8:11], v[152:155], v[212:215], v[8:11]
	v_mfma_f32_16x16x32_bf16 v[2:5], v[160:163], v[212:215], v[4:7]
	v_mfma_f32_16x16x32_bf16 v[56:59], v[156:159], v[172:175], v[56:59]
	v_mfma_f32_16x16x32_bf16 v[52:55], v[164:167], v[172:175], v[52:55]
	v_mfma_f32_16x16x32_bf16 v[40:43], v[156:159], v[180:183], v[40:43]
	v_mfma_f32_16x16x32_bf16 v[36:39], v[164:167], v[180:183], v[36:39]
	v_mfma_f32_16x16x32_bf16 v[24:27], v[156:159], v[188:191], v[24:27]
	v_mfma_f32_16x16x32_bf16 v[20:23], v[164:167], v[188:191], v[20:23]
	v_mfma_f32_16x16x32_bf16 v[8:11], v[156:159], v[216:219], v[8:11]
	v_mfma_f32_16x16x32_bf16 v[2:5], v[164:167], v[216:219], v[2:5]
	s_barrier
	s_setprio 0
	s_add_i32 s85, 0, 0x18000
	v_add_u32_e32 v0, s85, v243
	s_add_i32 s86, 0, 0x1c000
	ds_read_b128 v[128:131], v0
	ds_read_b128 v[132:135], v0 offset:1024
	ds_read_b128 v[136:139], v0 offset:2048
	ds_read_b128 v[140:143], v0 offset:3072
	v_add_u32_e32 v0, s86, v243
	ds_read_b128 v[152:155], v0
	ds_read_b128 v[156:159], v0 offset:1024
	ds_read_b128 v[160:163], v0 offset:2048
	ds_read_b128 v[164:167], v0 offset:3072
	s_add_u32 s38, s38, 0xe0000
	s_addc_u32 s39, s39, 0
	s_mov_b32 m0, s55
	v_lshl_add_u64 v[6:7], s[38:39], 0, v[206:207]
	ds_read_b128 v[168:171], v245 offset:32768
	ds_read_b128 v[172:175], v245 offset:33792
	ds_read_b128 v[176:179], v245 offset:34816
	ds_read_b128 v[180:183], v245 offset:35840
	ds_read_b128 v[184:187], v245 offset:36864
	ds_read_b128 v[188:191], v245 offset:37888
	ds_read_b128 v[212:215], v245 offset:38912
	ds_read_b128 v[216:219], v245 offset:39936
	global_load_lds_dwordx4 v[6:7], off
	v_lshl_add_u64 v[6:7], s[38:39], 0, v[202:203]
	s_mov_b32 m0, s56
	s_nop 0
	global_load_lds_dwordx4 v[6:7], off
	s_waitcnt vmcnt(8)
	s_waitcnt lgkmcnt(0)
	s_setprio 1
	s_barrier
	v_mfma_f32_16x16x32_bf16 v[148:151], v[128:131], v[168:171], v[148:151]
	v_mfma_f32_16x16x32_bf16 v[144:147], v[136:139], v[168:171], v[144:147]
	v_mfma_f32_16x16x32_bf16 v[112:115], v[128:131], v[176:179], v[112:115]
	v_mfma_f32_16x16x32_bf16 v[108:111], v[136:139], v[176:179], v[108:111]
	v_mfma_f32_16x16x32_bf16 v[96:99], v[128:131], v[184:187], v[96:99]
	v_mfma_f32_16x16x32_bf16 v[92:95], v[136:139], v[184:187], v[92:95]
	v_mfma_f32_16x16x32_bf16 v[80:83], v[128:131], v[212:215], v[80:83]
	v_mfma_f32_16x16x32_bf16 v[76:79], v[136:139], v[212:215], v[76:79]
	v_mfma_f32_16x16x32_bf16 v[148:151], v[132:135], v[172:175], v[148:151]
	v_mfma_f32_16x16x32_bf16 v[144:147], v[140:143], v[172:175], v[144:147]
	v_mfma_f32_16x16x32_bf16 v[112:115], v[132:135], v[180:183], v[112:115]
	v_mfma_f32_16x16x32_bf16 v[108:111], v[140:143], v[180:183], v[108:111]
	v_mfma_f32_16x16x32_bf16 v[96:99], v[132:135], v[188:191], v[96:99]
	v_mfma_f32_16x16x32_bf16 v[92:95], v[140:143], v[188:191], v[92:95]
	v_mfma_f32_16x16x32_bf16 v[80:83], v[132:135], v[216:219], v[80:83]
	v_mfma_f32_16x16x32_bf16 v[76:79], v[140:143], v[216:219], v[76:79]
	v_mfma_f32_16x16x32_bf16 v[120:123], v[152:155], v[168:171], v[120:123]
	v_mfma_f32_16x16x32_bf16 v[116:119], v[160:163], v[168:171], v[116:119]
	v_mfma_f32_16x16x32_bf16 v[104:107], v[152:155], v[176:179], v[104:107]
	v_mfma_f32_16x16x32_bf16 v[100:103], v[160:163], v[176:179], v[100:103]
	v_mfma_f32_16x16x32_bf16 v[88:91], v[152:155], v[184:187], v[88:91]
	v_mfma_f32_16x16x32_bf16 v[84:87], v[160:163], v[184:187], v[84:87]
	v_mfma_f32_16x16x32_bf16 v[72:75], v[152:155], v[212:215], v[72:75]
	v_mfma_f32_16x16x32_bf16 v[68:71], v[160:163], v[212:215], v[68:71]
	v_mfma_f32_16x16x32_bf16 v[120:123], v[156:159], v[172:175], v[120:123]
	v_mfma_f32_16x16x32_bf16 v[116:119], v[164:167], v[172:175], v[116:119]
	v_mfma_f32_16x16x32_bf16 v[104:107], v[156:159], v[180:183], v[104:107]
	v_mfma_f32_16x16x32_bf16 v[100:103], v[164:167], v[180:183], v[100:103]
	v_mfma_f32_16x16x32_bf16 v[88:91], v[156:159], v[188:191], v[88:91]
	v_mfma_f32_16x16x32_bf16 v[84:87], v[164:167], v[188:191], v[84:87]
	v_mfma_f32_16x16x32_bf16 v[72:75], v[156:159], v[216:219], v[72:75]
	v_mfma_f32_16x16x32_bf16 v[68:71], v[164:167], v[216:219], v[68:71]
	s_barrier
	s_setprio 0
	s_add_i32 s38, s85, s40
	v_lshl_add_u64 v[6:7], v[194:195], 0, s[90:91]
	s_mov_b32 m0, s38
	ds_read_b128 v[168:171], v245 offset:49152
	ds_read_b128 v[172:175], v245 offset:50176
	ds_read_b128 v[176:179], v245 offset:51200
	ds_read_b128 v[180:183], v245 offset:52224
	ds_read_b128 v[184:187], v245 offset:53248
	ds_read_b128 v[188:191], v245 offset:54272
	ds_read_b128 v[212:215], v245 offset:55296
	ds_read_b128 v[216:219], v245 offset:56320
	global_load_lds_dwordx4 v[6:7], off
	s_add_i32 m0, s38, 0x2000
	s_add_u32 s36, s36, 0x40080
	v_lshl_add_u64 v[6:7], v[198:199], 0, s[90:91]
	s_addc_u32 s37, s37, 0
	s_add_i32 s38, s86, s40
	global_load_lds_dwordx4 v[6:7], off
	v_lshl_add_u64 v[6:7], s[36:37], 0, v[204:205]
	s_mov_b32 m0, s38
	s_nop 0
	global_load_lds_dwordx4 v[6:7], off
	v_lshl_add_u64 v[6:7], s[36:37], 0, v[192:193]
	s_add_i32 m0, s38, 0x2000
	s_nop 0
	global_load_lds_dwordx4 v[6:7], off
	v_lshl_add_u64 v[6:7], s[34:35], 0, v[206:207]
	s_mov_b32 m0, s57
	s_nop 0
	global_load_lds_dwordx4 v[6:7], off
	v_lshl_add_u64 v[6:7], s[34:35], 0, v[202:203]
	s_mov_b32 m0, s58
	s_nop 0
	global_load_lds_dwordx4 v[6:7], off
	s_waitcnt vmcnt(8)
	s_waitcnt lgkmcnt(0)
	s_setprio 1
	s_barrier
	v_mfma_f32_16x16x32_bf16 v[64:67], v[128:131], v[168:171], v[64:67]
	v_mfma_f32_16x16x32_bf16 v[60:63], v[136:139], v[168:171], v[60:63]
	v_mfma_f32_16x16x32_bf16 v[48:51], v[128:131], v[176:179], v[48:51]
	v_mfma_f32_16x16x32_bf16 v[44:47], v[136:139], v[176:179], v[44:47]
	v_mfma_f32_16x16x32_bf16 v[32:35], v[128:131], v[184:187], v[32:35]
	v_mfma_f32_16x16x32_bf16 v[28:31], v[136:139], v[184:187], v[28:31]
	v_mfma_f32_16x16x32_bf16 v[16:19], v[128:131], v[212:215], v[16:19]
	v_mfma_f32_16x16x32_bf16 v[12:15], v[136:139], v[212:215], v[12:15]
	v_mfma_f32_16x16x32_bf16 v[64:67], v[132:135], v[172:175], v[64:67]
	v_mfma_f32_16x16x32_bf16 v[60:63], v[140:143], v[172:175], v[60:63]
	v_mfma_f32_16x16x32_bf16 v[48:51], v[132:135], v[180:183], v[48:51]
	v_mfma_f32_16x16x32_bf16 v[44:47], v[140:143], v[180:183], v[44:47]
	v_mfma_f32_16x16x32_bf16 v[32:35], v[132:135], v[188:191], v[32:35]
	v_mfma_f32_16x16x32_bf16 v[28:31], v[140:143], v[188:191], v[28:31]
	v_mfma_f32_16x16x32_bf16 v[16:19], v[132:135], v[216:219], v[16:19]
	v_mfma_f32_16x16x32_bf16 v[12:15], v[140:143], v[216:219], v[12:15]
	v_mfma_f32_16x16x32_bf16 v[56:59], v[152:155], v[168:171], v[56:59]
	v_mfma_f32_16x16x32_bf16 v[52:55], v[160:163], v[168:171], v[52:55]
	v_mfma_f32_16x16x32_bf16 v[40:43], v[152:155], v[176:179], v[40:43]
	v_mfma_f32_16x16x32_bf16 v[36:39], v[160:163], v[176:179], v[36:39]
	v_mfma_f32_16x16x32_bf16 v[24:27], v[152:155], v[184:187], v[24:27]
	v_mfma_f32_16x16x32_bf16 v[20:23], v[160:163], v[184:187], v[20:23]
	v_mfma_f32_16x16x32_bf16 v[6:9], v[152:155], v[212:215], v[8:11]
	v_mfma_f32_16x16x32_bf16 v[2:5], v[160:163], v[212:215], v[2:5]
	v_mfma_f32_16x16x32_bf16 v[56:59], v[156:159], v[172:175], v[56:59]
	v_mfma_f32_16x16x32_bf16 v[52:55], v[164:167], v[172:175], v[52:55]
	v_mfma_f32_16x16x32_bf16 v[40:43], v[156:159], v[180:183], v[40:43]
	v_mfma_f32_16x16x32_bf16 v[36:39], v[164:167], v[180:183], v[36:39]
	v_mfma_f32_16x16x32_bf16 v[24:27], v[156:159], v[188:191], v[24:27]
	v_mfma_f32_16x16x32_bf16 v[20:23], v[164:167], v[188:191], v[20:23]
	v_mfma_f32_16x16x32_bf16 v[8:11], v[156:159], v[216:219], v[6:9]
	v_mfma_f32_16x16x32_bf16 v[4:7], v[164:167], v[216:219], v[2:5]
	s_barrier
	s_setprio 0
	s_add_u32 s12, s12, 0x100
	s_addc_u32 s13, s13, 0
	s_cmp_gt_u32 s78, 13
	s_cbranch_scc1 .LBB0_588

.LBB0_675:
	s_add_u32 s4, s30, s34
	s_addc_u32 s5, s31, s35
	s_add_u32 s40, s4, 0x100
	s_addc_u32 s41, s5, 0
	s_add_u32 s38, s78, s34
	s_addc_u32 s39, s85, s35
	s_add_u32 s4, s4, 0x180
	s_addc_u32 s5, s5, 0
	s_add_i32 s87, 0, 0x10000
	s_add_i32 s65, 0, 0x14000
	v_add_u32_e32 v0, s87, v148
	ds_read_b128 v[150:153], v0
	ds_read_b128 v[154:157], v0 offset:1024
	ds_read_b128 v[158:161], v0 offset:2048
	ds_read_b128 v[162:165], v0 offset:3072
	v_add_u32_e32 v0, s65, v148
	ds_read_b128 v[166:169], v0
	ds_read_b128 v[170:173], v0 offset:1024
	ds_read_b128 v[174:177], v0 offset:2048
	ds_read_b128 v[178:181], v0 offset:3072
	s_cmpk_eq_i32 s34, 0x700
	s_cselect_b32 s37, s76, s5
	s_cselect_b32 s36, s75, s4
	s_cselect_b32 s39, s23, s39
	s_cselect_b32 s38, s74, s38
	s_cselect_b32 s41, s25, s41
	s_cselect_b32 s40, s73, s40
	v_lshl_add_u64 v[194:195], v[144:145], 0, s[34:35]
	s_add_i32 m0, s55, 0xc000
	ds_read_b128 v[182:185], v149
	ds_read_b128 v[186:189], v149 offset:1024
	ds_read_b128 v[190:193], v149 offset:2048
	ds_read_b128 v[202:205], v149 offset:3072
	ds_read_b128 v[206:209], v149 offset:4096
	ds_read_b128 v[210:213], v149 offset:5120
	ds_read_b128 v[214:217], v149 offset:6144
	ds_read_b128 v[218:221], v149 offset:7168
	global_load_lds_dwordx4 v[194:195], off
	v_lshl_add_u64 v[194:195], v[146:147], 0, s[34:35]
	s_add_i32 m0, s55, 0xe000
	s_nop 0
	global_load_lds_dwordx4 v[194:195], off
	s_waitcnt vmcnt(8)
	s_waitcnt lgkmcnt(0)
	s_setprio 1
	s_barrier
	v_mfma_f32_16x16x32_bf16 v[126:129], v[150:153], v[182:185], v[126:129]
	v_mfma_f32_16x16x32_bf16 v[122:125], v[158:161], v[182:185], v[122:125]
	v_mfma_f32_16x16x32_bf16 v[110:113], v[150:153], v[190:193], v[110:113]
	v_mfma_f32_16x16x32_bf16 v[106:109], v[158:161], v[190:193], v[106:109]
	v_mfma_f32_16x16x32_bf16 v[94:97], v[150:153], v[206:209], v[94:97]
	v_mfma_f32_16x16x32_bf16 v[90:93], v[158:161], v[206:209], v[90:93]
	v_mfma_f32_16x16x32_bf16 v[78:81], v[150:153], v[214:217], v[78:81]
	v_mfma_f32_16x16x32_bf16 v[74:77], v[158:161], v[214:217], v[74:77]
	v_mfma_f32_16x16x32_bf16 v[126:129], v[154:157], v[186:189], v[126:129]
	v_mfma_f32_16x16x32_bf16 v[122:125], v[162:165], v[186:189], v[122:125]
	v_mfma_f32_16x16x32_bf16 v[110:113], v[154:157], v[202:205], v[110:113]
	v_mfma_f32_16x16x32_bf16 v[106:109], v[162:165], v[202:205], v[106:109]
	v_mfma_f32_16x16x32_bf16 v[94:97], v[154:157], v[210:213], v[94:97]
	v_mfma_f32_16x16x32_bf16 v[90:93], v[162:165], v[210:213], v[90:93]
	v_mfma_f32_16x16x32_bf16 v[78:81], v[154:157], v[218:221], v[78:81]
	v_mfma_f32_16x16x32_bf16 v[74:77], v[162:165], v[218:221], v[74:77]
	v_mfma_f32_16x16x32_bf16 v[118:121], v[166:169], v[182:185], v[118:121]
	v_mfma_f32_16x16x32_bf16 v[114:117], v[174:177], v[182:185], v[114:117]
	v_mfma_f32_16x16x32_bf16 v[102:105], v[166:169], v[190:193], v[102:105]
	v_mfma_f32_16x16x32_bf16 v[98:101], v[174:177], v[190:193], v[98:101]
	v_mfma_f32_16x16x32_bf16 v[86:89], v[166:169], v[206:209], v[86:89]
	v_mfma_f32_16x16x32_bf16 v[82:85], v[174:177], v[206:209], v[82:85]
	v_mfma_f32_16x16x32_bf16 v[70:73], v[166:169], v[214:217], v[70:73]
	v_mfma_f32_16x16x32_bf16 v[66:69], v[174:177], v[214:217], v[66:69]
	v_mfma_f32_16x16x32_bf16 v[118:121], v[170:173], v[186:189], v[118:121]
	v_mfma_f32_16x16x32_bf16 v[114:117], v[178:181], v[186:189], v[114:117]
	v_mfma_f32_16x16x32_bf16 v[102:105], v[170:173], v[202:205], v[102:105]
	v_mfma_f32_16x16x32_bf16 v[98:101], v[178:181], v[202:205], v[98:101]
	v_mfma_f32_16x16x32_bf16 v[86:89], v[170:173], v[210:213], v[86:89]
	v_mfma_f32_16x16x32_bf16 v[82:85], v[178:181], v[210:213], v[82:85]
	v_mfma_f32_16x16x32_bf16 v[70:73], v[170:173], v[218:221], v[70:73]
	v_mfma_f32_16x16x32_bf16 v[66:69], v[178:181], v[218:221], v[66:69]
	s_barrier
	s_setprio 0
	s_add_i32 s4, s87, s51
	v_lshl_add_u64 v[194:195], s[38:39], 0, v[134:135]
	s_mov_b32 m0, s4
	ds_read_b128 v[182:185], v149 offset:16384
	ds_read_b128 v[186:189], v149 offset:17408
	ds_read_b128 v[190:193], v149 offset:18432
	ds_read_b128 v[202:205], v149 offset:19456
	ds_read_b128 v[206:209], v149 offset:20480
	ds_read_b128 v[210:213], v149 offset:21504
	ds_read_b128 v[214:217], v149 offset:22528
	ds_read_b128 v[218:221], v149 offset:23552
	global_load_lds_dwordx4 v[194:195], off
	s_add_i32 m0, s4, 0x2000
	s_add_u32 vcc_lo, s38, 0x40000
	v_lshl_add_u64 v[198:199], s[38:39], 0, v[130:131]
	s_addc_u32 vcc_hi, s39, 0
	s_add_i32 s4, s65, s51
	global_load_lds_dwordx4 v[198:199], off
	v_lshl_add_u64 v[222:223], vcc, 0, v[134:135]
	s_mov_b32 m0, s4
	s_nop 0
	global_load_lds_dwordx4 v[222:223], off
	v_lshl_add_u64 v[222:223], vcc, 0, v[130:131]
	s_add_i32 m0, s4, 0x2000
	s_nop 0
	global_load_lds_dwordx4 v[222:223], off
	v_lshl_add_u64 v[222:223], s[40:41], 0, v[136:137]
	s_mov_b32 m0, s55
	s_nop 0
	global_load_lds_dwordx4 v[222:223], off
	v_lshl_add_u64 v[222:223], s[40:41], 0, v[132:133]
	s_mov_b32 m0, s56
	s_nop 0
	global_load_lds_dwordx4 v[222:223], off
	s_waitcnt vmcnt(8)
	s_waitcnt lgkmcnt(0)
	s_setprio 1
	s_barrier
	v_mfma_f32_16x16x32_bf16 v[62:65], v[150:153], v[182:185], v[62:65]
	v_mfma_f32_16x16x32_bf16 v[58:61], v[158:161], v[182:185], v[58:61]
	v_mfma_f32_16x16x32_bf16 v[46:49], v[150:153], v[190:193], v[46:49]
	v_mfma_f32_16x16x32_bf16 v[42:45], v[158:161], v[190:193], v[42:45]
	v_mfma_f32_16x16x32_bf16 v[30:33], v[150:153], v[206:209], v[30:33]
	v_mfma_f32_16x16x32_bf16 v[26:29], v[158:161], v[206:209], v[26:29]
	v_mfma_f32_16x16x32_bf16 v[14:17], v[150:153], v[214:217], v[14:17]
	v_mfma_f32_16x16x32_bf16 v[10:13], v[158:161], v[214:217], v[10:13]
	v_mfma_f32_16x16x32_bf16 v[62:65], v[154:157], v[186:189], v[62:65]
	v_mfma_f32_16x16x32_bf16 v[58:61], v[162:165], v[186:189], v[58:61]
	v_mfma_f32_16x16x32_bf16 v[46:49], v[154:157], v[202:205], v[46:49]
	v_mfma_f32_16x16x32_bf16 v[42:45], v[162:165], v[202:205], v[42:45]
	v_mfma_f32_16x16x32_bf16 v[30:33], v[154:157], v[210:213], v[30:33]
	v_mfma_f32_16x16x32_bf16 v[26:29], v[162:165], v[210:213], v[26:29]
	v_mfma_f32_16x16x32_bf16 v[14:17], v[154:157], v[218:221], v[14:17]
	v_mfma_f32_16x16x32_bf16 v[10:13], v[162:165], v[218:221], v[10:13]
	v_mfma_f32_16x16x32_bf16 v[54:57], v[166:169], v[182:185], v[54:57]
	v_mfma_f32_16x16x32_bf16 v[50:53], v[174:177], v[182:185], v[50:53]
	v_mfma_f32_16x16x32_bf16 v[38:41], v[166:169], v[190:193], v[38:41]
	v_mfma_f32_16x16x32_bf16 v[34:37], v[174:177], v[190:193], v[34:37]
	v_mfma_f32_16x16x32_bf16 v[22:25], v[166:169], v[206:209], v[22:25]
	v_mfma_f32_16x16x32_bf16 v[18:21], v[174:177], v[206:209], v[18:21]
	v_mfma_f32_16x16x32_bf16 v[6:9], v[166:169], v[214:217], v[6:9]
	v_mfma_f32_16x16x32_bf16 v[2:5], v[174:177], v[214:217], v[2:5]
	v_mfma_f32_16x16x32_bf16 v[54:57], v[170:173], v[186:189], v[54:57]
	v_mfma_f32_16x16x32_bf16 v[50:53], v[178:181], v[186:189], v[50:53]
	v_mfma_f32_16x16x32_bf16 v[38:41], v[170:173], v[202:205], v[38:41]
	v_mfma_f32_16x16x32_bf16 v[34:37], v[178:181], v[202:205], v[34:37]
	v_mfma_f32_16x16x32_bf16 v[22:25], v[170:173], v[210:213], v[22:25]
	v_mfma_f32_16x16x32_bf16 v[18:21], v[178:181], v[210:213], v[18:21]
	v_mfma_f32_16x16x32_bf16 v[6:9], v[170:173], v[218:221], v[6:9]
	v_mfma_f32_16x16x32_bf16 v[2:5], v[178:181], v[218:221], v[2:5]
	s_barrier
	s_setprio 0
	s_add_i32 s4, 0, 0x18000
	v_add_u32_e32 v0, s4, v148
	s_add_i32 s5, 0, 0x1c000
	ds_read_b128 v[150:153], v0
	ds_read_b128 v[154:157], v0 offset:1024
	ds_read_b128 v[158:161], v0 offset:2048
	ds_read_b128 v[162:165], v0 offset:3072
	v_add_u32_e32 v0, s5, v148
	ds_read_b128 v[166:169], v0
	ds_read_b128 v[170:173], v0 offset:1024
	ds_read_b128 v[174:177], v0 offset:2048
	ds_read_b128 v[178:181], v0 offset:3072
	s_add_u32 s40, s40, 0x40000
	s_addc_u32 s41, s41, 0
	s_mov_b32 m0, s57
	v_lshl_add_u64 v[222:223], s[40:41], 0, v[136:137]
	ds_read_b128 v[182:185], v149 offset:32768
	ds_read_b128 v[186:189], v149 offset:33792
	ds_read_b128 v[190:193], v149 offset:34816
	ds_read_b128 v[202:205], v149 offset:35840
	ds_read_b128 v[206:209], v149 offset:36864
	ds_read_b128 v[210:213], v149 offset:37888
	ds_read_b128 v[214:217], v149 offset:38912
	ds_read_b128 v[218:221], v149 offset:39936
	global_load_lds_dwordx4 v[222:223], off
	v_lshl_add_u64 v[222:223], s[40:41], 0, v[132:133]
	s_mov_b32 m0, s58
	s_nop 0
	global_load_lds_dwordx4 v[222:223], off
	s_waitcnt vmcnt(8)
	s_waitcnt lgkmcnt(0)
	s_setprio 1
	s_barrier
	v_mfma_f32_16x16x32_bf16 v[126:129], v[150:153], v[182:185], v[126:129]
	v_mfma_f32_16x16x32_bf16 v[122:125], v[158:161], v[182:185], v[122:125]
	v_mfma_f32_16x16x32_bf16 v[110:113], v[150:153], v[190:193], v[110:113]
	v_mfma_f32_16x16x32_bf16 v[106:109], v[158:161], v[190:193], v[106:109]
	v_mfma_f32_16x16x32_bf16 v[94:97], v[150:153], v[206:209], v[94:97]
	v_mfma_f32_16x16x32_bf16 v[90:93], v[158:161], v[206:209], v[90:93]
	v_mfma_f32_16x16x32_bf16 v[78:81], v[150:153], v[214:217], v[78:81]
	v_mfma_f32_16x16x32_bf16 v[74:77], v[158:161], v[214:217], v[74:77]
	v_mfma_f32_16x16x32_bf16 v[126:129], v[154:157], v[186:189], v[126:129]
	v_mfma_f32_16x16x32_bf16 v[122:125], v[162:165], v[186:189], v[122:125]
	v_mfma_f32_16x16x32_bf16 v[110:113], v[154:157], v[202:205], v[110:113]
	v_mfma_f32_16x16x32_bf16 v[106:109], v[162:165], v[202:205], v[106:109]
	v_mfma_f32_16x16x32_bf16 v[94:97], v[154:157], v[210:213], v[94:97]
	v_mfma_f32_16x16x32_bf16 v[90:93], v[162:165], v[210:213], v[90:93]
	v_mfma_f32_16x16x32_bf16 v[78:81], v[154:157], v[218:221], v[78:81]
	v_mfma_f32_16x16x32_bf16 v[74:77], v[162:165], v[218:221], v[74:77]
	v_mfma_f32_16x16x32_bf16 v[118:121], v[166:169], v[182:185], v[118:121]
	v_mfma_f32_16x16x32_bf16 v[114:117], v[174:177], v[182:185], v[114:117]
	v_mfma_f32_16x16x32_bf16 v[102:105], v[166:169], v[190:193], v[102:105]
	v_mfma_f32_16x16x32_bf16 v[98:101], v[174:177], v[190:193], v[98:101]
	v_mfma_f32_16x16x32_bf16 v[86:89], v[166:169], v[206:209], v[86:89]
	v_mfma_f32_16x16x32_bf16 v[82:85], v[174:177], v[206:209], v[82:85]
	v_mfma_f32_16x16x32_bf16 v[70:73], v[166:169], v[214:217], v[70:73]
	v_mfma_f32_16x16x32_bf16 v[66:69], v[174:177], v[214:217], v[66:69]
	v_mfma_f32_16x16x32_bf16 v[118:121], v[170:173], v[186:189], v[118:121]
	v_mfma_f32_16x16x32_bf16 v[114:117], v[178:181], v[186:189], v[114:117]
	v_mfma_f32_16x16x32_bf16 v[102:105], v[170:173], v[202:205], v[102:105]
	v_mfma_f32_16x16x32_bf16 v[98:101], v[178:181], v[202:205], v[98:101]
	v_mfma_f32_16x16x32_bf16 v[86:89], v[170:173], v[210:213], v[86:89]
	v_mfma_f32_16x16x32_bf16 v[82:85], v[178:181], v[210:213], v[82:85]
	v_mfma_f32_16x16x32_bf16 v[70:73], v[170:173], v[218:221], v[70:73]
	v_mfma_f32_16x16x32_bf16 v[66:69], v[178:181], v[218:221], v[66:69]
	s_barrier
	s_setprio 0
	s_add_i32 s4, s4, s51
	v_lshl_add_u64 v[194:195], v[194:195], 0, s[90:91]
	s_mov_b32 m0, s4
	ds_read_b128 v[182:185], v149 offset:49152
	ds_read_b128 v[186:189], v149 offset:50176
	ds_read_b128 v[190:193], v149 offset:51200
	ds_read_b128 v[202:205], v149 offset:52224
	ds_read_b128 v[206:209], v149 offset:53248
	ds_read_b128 v[210:213], v149 offset:54272
	ds_read_b128 v[214:217], v149 offset:55296
	ds_read_b128 v[218:221], v149 offset:56320
	global_load_lds_dwordx4 v[194:195], off
	s_add_i32 m0, s4, 0x2000
	s_add_u32 s38, s38, 0x40080
	v_lshl_add_u64 v[194:195], v[198:199], 0, s[90:91]
	s_addc_u32 s39, s39, 0
	s_add_i32 s4, s5, s51
	global_load_lds_dwordx4 v[194:195], off
	v_lshl_add_u64 v[194:195], s[38:39], 0, v[134:135]
	s_mov_b32 m0, s4
	s_nop 0
	global_load_lds_dwordx4 v[194:195], off
	v_lshl_add_u64 v[194:195], s[38:39], 0, v[130:131]
	s_add_i32 m0, s4, 0x2000
	s_nop 0
	global_load_lds_dwordx4 v[194:195], off
	v_lshl_add_u64 v[194:195], s[36:37], 0, v[136:137]
	s_mov_b32 m0, s68
	s_nop 0
	global_load_lds_dwordx4 v[194:195], off
	v_lshl_add_u64 v[194:195], s[36:37], 0, v[132:133]
	s_mov_b32 m0, s69
	s_nop 0
	global_load_lds_dwordx4 v[194:195], off
	s_waitcnt vmcnt(8)
	s_waitcnt lgkmcnt(0)
	s_setprio 1
	s_barrier
	v_mfma_f32_16x16x32_bf16 v[62:65], v[150:153], v[182:185], v[62:65]
	v_mfma_f32_16x16x32_bf16 v[58:61], v[158:161], v[182:185], v[58:61]
	v_mfma_f32_16x16x32_bf16 v[46:49], v[150:153], v[190:193], v[46:49]
	v_mfma_f32_16x16x32_bf16 v[42:45], v[158:161], v[190:193], v[42:45]
	v_mfma_f32_16x16x32_bf16 v[30:33], v[150:153], v[206:209], v[30:33]
	v_mfma_f32_16x16x32_bf16 v[26:29], v[158:161], v[206:209], v[26:29]
	v_mfma_f32_16x16x32_bf16 v[14:17], v[150:153], v[214:217], v[14:17]
	v_mfma_f32_16x16x32_bf16 v[10:13], v[158:161], v[214:217], v[10:13]
	v_mfma_f32_16x16x32_bf16 v[62:65], v[154:157], v[186:189], v[62:65]
	v_mfma_f32_16x16x32_bf16 v[58:61], v[162:165], v[186:189], v[58:61]
	v_mfma_f32_16x16x32_bf16 v[46:49], v[154:157], v[202:205], v[46:49]
	v_mfma_f32_16x16x32_bf16 v[42:45], v[162:165], v[202:205], v[42:45]
	v_mfma_f32_16x16x32_bf16 v[30:33], v[154:157], v[210:213], v[30:33]
	v_mfma_f32_16x16x32_bf16 v[26:29], v[162:165], v[210:213], v[26:29]
	v_mfma_f32_16x16x32_bf16 v[14:17], v[154:157], v[218:221], v[14:17]
	v_mfma_f32_16x16x32_bf16 v[10:13], v[162:165], v[218:221], v[10:13]
	v_mfma_f32_16x16x32_bf16 v[54:57], v[166:169], v[182:185], v[54:57]
	v_mfma_f32_16x16x32_bf16 v[50:53], v[174:177], v[182:185], v[50:53]
	v_mfma_f32_16x16x32_bf16 v[38:41], v[166:169], v[190:193], v[38:41]
	v_mfma_f32_16x16x32_bf16 v[34:37], v[174:177], v[190:193], v[34:37]
	v_mfma_f32_16x16x32_bf16 v[22:25], v[166:169], v[206:209], v[22:25]
	v_mfma_f32_16x16x32_bf16 v[18:21], v[174:177], v[206:209], v[18:21]
	v_mfma_f32_16x16x32_bf16 v[6:9], v[166:169], v[214:217], v[6:9]
	v_mfma_f32_16x16x32_bf16 v[2:5], v[174:177], v[214:217], v[2:5]
	v_mfma_f32_16x16x32_bf16 v[54:57], v[170:173], v[186:189], v[54:57]
	v_mfma_f32_16x16x32_bf16 v[50:53], v[178:181], v[186:189], v[50:53]
	v_mfma_f32_16x16x32_bf16 v[38:41], v[170:173], v[202:205], v[38:41]
	v_mfma_f32_16x16x32_bf16 v[34:37], v[178:181], v[202:205], v[34:37]
	v_mfma_f32_16x16x32_bf16 v[22:25], v[170:173], v[210:213], v[22:25]
	v_mfma_f32_16x16x32_bf16 v[18:21], v[178:181], v[210:213], v[18:21]
	v_mfma_f32_16x16x32_bf16 v[6:9], v[170:173], v[218:221], v[6:9]
	v_mfma_f32_16x16x32_bf16 v[2:5], v[178:181], v[218:221], v[2:5]
	s_barrier
	s_setprio 0
	s_add_i32 s86, s86, 2
	s_add_u32 s34, s34, 0x100
	s_addc_u32 s35, s35, 0
	s_cmp_gt_u32 s86, 13
	s_cbranch_scc0 .LBB0_675
	s_and_b64 vcc, exec, s[20:21]
	s_cbranch_vccz .LBB0_678
	s_barrier

.LBB0_773:
	s_add_u32 s4, s30, s34
	s_addc_u32 s5, s31, s35
	s_add_u32 s40, s4, 0x100
	s_addc_u32 s41, s5, 0
	s_add_u32 s38, s78, s34
	s_addc_u32 s39, s85, s35
	s_add_u32 s4, s4, 0x180
	s_addc_u32 s5, s5, 0
	s_add_i32 s65, 0, 0x10000
	s_add_i32 s87, 0, 0x14000
	v_add_u32_e32 v138, s65, v231
	v_add_u32_e32 v162, s87, v231
	ds_read_b128 v[126:129], v138
	ds_read_b128 v[130:133], v138 offset:1024
	ds_read_b128 v[134:137], v138 offset:2048
	ds_read_b128 v[138:141], v138 offset:3072
	ds_read_b128 v[142:145], v162
	ds_read_b128 v[146:149], v162 offset:1024
	ds_read_b128 v[158:161], v162 offset:2048
	ds_read_b128 v[162:165], v162 offset:3072
	s_cmpk_eq_i32 s34, 0x700
	s_cselect_b32 s37, s76, s5
	s_cselect_b32 s36, s75, s4
	s_cselect_b32 s39, s23, s39
	s_cselect_b32 s38, s74, s38
	s_cselect_b32 s41, s25, s41
	s_cselect_b32 s40, s73, s40
	v_lshl_add_u64 v[194:195], v[118:119], 0, s[34:35]
	s_add_i32 m0, s56, 0xc000
	ds_read_b128 v[166:169], v242
	ds_read_b128 v[170:173], v242 offset:1024
	ds_read_b128 v[174:177], v242 offset:2048
	ds_read_b128 v[178:181], v242 offset:3072
	ds_read_b128 v[182:185], v242 offset:4096
	ds_read_b128 v[186:189], v242 offset:5120
	ds_read_b128 v[208:211], v242 offset:6144
	ds_read_b128 v[212:215], v242 offset:7168
	global_load_lds_dwordx4 v[194:195], off
	v_lshl_add_u64 v[194:195], v[120:121], 0, s[34:35]
	s_add_i32 m0, s56, 0xe000
	s_nop 0
	global_load_lds_dwordx4 v[194:195], off
	s_waitcnt vmcnt(8)
	s_waitcnt lgkmcnt(0)
	s_setprio 1
	s_barrier
	v_mfma_f32_16x16x32_bf16 v[154:157], v[126:129], v[166:169], v[154:157]
	v_mfma_f32_16x16x32_bf16 v[150:153], v[134:137], v[166:169], v[150:153]
	v_mfma_f32_16x16x32_bf16 v[110:113], v[126:129], v[174:177], v[110:113]
	v_mfma_f32_16x16x32_bf16 v[106:109], v[134:137], v[174:177], v[106:109]
	v_mfma_f32_16x16x32_bf16 v[94:97], v[126:129], v[182:185], v[94:97]
	v_mfma_f32_16x16x32_bf16 v[90:93], v[134:137], v[182:185], v[90:93]
	v_mfma_f32_16x16x32_bf16 v[78:81], v[126:129], v[208:211], v[78:81]
	v_mfma_f32_16x16x32_bf16 v[74:77], v[134:137], v[208:211], v[74:77]
	v_mfma_f32_16x16x32_bf16 v[154:157], v[130:133], v[170:173], v[154:157]
	v_mfma_f32_16x16x32_bf16 v[150:153], v[138:141], v[170:173], v[150:153]
	v_mfma_f32_16x16x32_bf16 v[110:113], v[130:133], v[178:181], v[110:113]
	v_mfma_f32_16x16x32_bf16 v[106:109], v[138:141], v[178:181], v[106:109]
	v_mfma_f32_16x16x32_bf16 v[94:97], v[130:133], v[186:189], v[94:97]
	v_mfma_f32_16x16x32_bf16 v[90:93], v[138:141], v[186:189], v[90:93]
	v_mfma_f32_16x16x32_bf16 v[78:81], v[130:133], v[212:215], v[78:81]
	v_mfma_f32_16x16x32_bf16 v[74:77], v[138:141], v[212:215], v[74:77]
	v_mfma_f32_16x16x32_bf16 v[122:125], v[142:145], v[166:169], v[122:125]
	v_mfma_f32_16x16x32_bf16 v[114:117], v[158:161], v[166:169], v[114:117]
	v_mfma_f32_16x16x32_bf16 v[102:105], v[142:145], v[174:177], v[102:105]
	v_mfma_f32_16x16x32_bf16 v[98:101], v[158:161], v[174:177], v[98:101]
	v_mfma_f32_16x16x32_bf16 v[86:89], v[142:145], v[182:185], v[86:89]
	v_mfma_f32_16x16x32_bf16 v[82:85], v[158:161], v[182:185], v[82:85]
	v_mfma_f32_16x16x32_bf16 v[70:73], v[142:145], v[208:211], v[70:73]
	v_mfma_f32_16x16x32_bf16 v[66:69], v[158:161], v[208:211], v[66:69]
	v_mfma_f32_16x16x32_bf16 v[122:125], v[146:149], v[170:173], v[122:125]
	v_mfma_f32_16x16x32_bf16 v[114:117], v[162:165], v[170:173], v[114:117]
	v_mfma_f32_16x16x32_bf16 v[102:105], v[146:149], v[178:181], v[102:105]
	v_mfma_f32_16x16x32_bf16 v[98:101], v[162:165], v[178:181], v[98:101]
	v_mfma_f32_16x16x32_bf16 v[86:89], v[146:149], v[186:189], v[86:89]
	v_mfma_f32_16x16x32_bf16 v[82:85], v[162:165], v[186:189], v[82:85]
	v_mfma_f32_16x16x32_bf16 v[70:73], v[146:149], v[212:215], v[70:73]
	v_mfma_f32_16x16x32_bf16 v[66:69], v[162:165], v[212:215], v[66:69]
	s_barrier
	s_setprio 0
	s_add_i32 s4, s65, s51
	v_lshl_add_u64 v[194:195], s[38:39], 0, v[0:1]
	s_mov_b32 m0, s4
	ds_read_b128 v[166:169], v242 offset:16384
	ds_read_b128 v[170:173], v242 offset:17408
	ds_read_b128 v[174:177], v242 offset:18432
	ds_read_b128 v[178:181], v242 offset:19456
	ds_read_b128 v[182:185], v242 offset:20480
	ds_read_b128 v[186:189], v242 offset:21504
	ds_read_b128 v[208:211], v242 offset:22528
	ds_read_b128 v[212:215], v242 offset:23552
	global_load_lds_dwordx4 v[194:195], off
	s_add_i32 m0, s4, 0x2000
	s_add_u32 vcc_lo, s38, 0x40000
	v_lshl_add_u64 v[198:199], s[38:39], 0, v[190:191]
	s_addc_u32 vcc_hi, s39, 0
	s_add_i32 s4, s87, s51
	global_load_lds_dwordx4 v[198:199], off
	v_lshl_add_u64 v[216:217], vcc, 0, v[0:1]
	s_mov_b32 m0, s4
	s_nop 0
	global_load_lds_dwordx4 v[216:217], off
	v_lshl_add_u64 v[216:217], vcc, 0, v[190:191]
	s_add_i32 m0, s4, 0x2000
	s_nop 0
	global_load_lds_dwordx4 v[216:217], off
	v_lshl_add_u64 v[216:217], s[40:41], 0, v[202:203]
	s_mov_b32 m0, s56
	s_nop 0
	global_load_lds_dwordx4 v[216:217], off
	v_lshl_add_u64 v[216:217], s[40:41], 0, v[192:193]
	s_mov_b32 m0, s57
	s_nop 0
	global_load_lds_dwordx4 v[216:217], off
	s_waitcnt vmcnt(8)
	s_waitcnt lgkmcnt(0)
	s_setprio 1
	s_barrier
	v_mfma_f32_16x16x32_bf16 v[62:65], v[126:129], v[166:169], v[62:65]
	v_mfma_f32_16x16x32_bf16 v[58:61], v[134:137], v[166:169], v[58:61]
	v_mfma_f32_16x16x32_bf16 v[46:49], v[126:129], v[174:177], v[46:49]
	v_mfma_f32_16x16x32_bf16 v[42:45], v[134:137], v[174:177], v[42:45]
	v_mfma_f32_16x16x32_bf16 v[30:33], v[126:129], v[182:185], v[30:33]
	v_mfma_f32_16x16x32_bf16 v[26:29], v[134:137], v[182:185], v[26:29]
	v_mfma_f32_16x16x32_bf16 v[14:17], v[126:129], v[208:211], v[14:17]
	v_mfma_f32_16x16x32_bf16 v[10:13], v[134:137], v[208:211], v[10:13]
	v_mfma_f32_16x16x32_bf16 v[62:65], v[130:133], v[170:173], v[62:65]
	v_mfma_f32_16x16x32_bf16 v[58:61], v[138:141], v[170:173], v[58:61]
	v_mfma_f32_16x16x32_bf16 v[46:49], v[130:133], v[178:181], v[46:49]
	v_mfma_f32_16x16x32_bf16 v[42:45], v[138:141], v[178:181], v[42:45]
	v_mfma_f32_16x16x32_bf16 v[30:33], v[130:133], v[186:189], v[30:33]
	v_mfma_f32_16x16x32_bf16 v[26:29], v[138:141], v[186:189], v[26:29]
	v_mfma_f32_16x16x32_bf16 v[14:17], v[130:133], v[212:215], v[14:17]
	v_mfma_f32_16x16x32_bf16 v[10:13], v[138:141], v[212:215], v[10:13]
	v_mfma_f32_16x16x32_bf16 v[54:57], v[142:145], v[166:169], v[54:57]
	v_mfma_f32_16x16x32_bf16 v[50:53], v[158:161], v[166:169], v[50:53]
	v_mfma_f32_16x16x32_bf16 v[38:41], v[142:145], v[174:177], v[38:41]
	v_mfma_f32_16x16x32_bf16 v[34:37], v[158:161], v[174:177], v[34:37]
	v_mfma_f32_16x16x32_bf16 v[22:25], v[142:145], v[182:185], v[22:25]
	v_mfma_f32_16x16x32_bf16 v[18:21], v[158:161], v[182:185], v[18:21]
	v_mfma_f32_16x16x32_bf16 v[6:9], v[142:145], v[208:211], v[6:9]
	v_mfma_f32_16x16x32_bf16 v[2:5], v[158:161], v[208:211], v[2:5]
	v_mfma_f32_16x16x32_bf16 v[54:57], v[146:149], v[170:173], v[54:57]
	v_mfma_f32_16x16x32_bf16 v[50:53], v[162:165], v[170:173], v[50:53]
	v_mfma_f32_16x16x32_bf16 v[38:41], v[146:149], v[178:181], v[38:41]
	v_mfma_f32_16x16x32_bf16 v[34:37], v[162:165], v[178:181], v[34:37]
	v_mfma_f32_16x16x32_bf16 v[22:25], v[146:149], v[186:189], v[22:25]
	v_mfma_f32_16x16x32_bf16 v[18:21], v[162:165], v[186:189], v[18:21]
	v_mfma_f32_16x16x32_bf16 v[6:9], v[146:149], v[212:215], v[6:9]
	v_mfma_f32_16x16x32_bf16 v[2:5], v[162:165], v[212:215], v[2:5]
	s_barrier
	s_setprio 0
	s_add_i32 s4, 0, 0x18000
	s_add_i32 s5, 0, 0x1c000
	v_add_u32_e32 v138, s4, v231
	v_add_u32_e32 v162, s5, v231
	ds_read_b128 v[126:129], v138
	ds_read_b128 v[130:133], v138 offset:1024
	ds_read_b128 v[134:137], v138 offset:2048
	ds_read_b128 v[138:141], v138 offset:3072
	ds_read_b128 v[142:145], v162
	ds_read_b128 v[146:149], v162 offset:1024
	ds_read_b128 v[158:161], v162 offset:2048
	ds_read_b128 v[162:165], v162 offset:3072
	s_add_u32 s40, s40, 0x40000
	s_addc_u32 s41, s41, 0
	s_mov_b32 m0, s58
	v_lshl_add_u64 v[216:217], s[40:41], 0, v[202:203]
	ds_read_b128 v[166:169], v242 offset:32768
	ds_read_b128 v[170:173], v242 offset:33792
	ds_read_b128 v[174:177], v242 offset:34816
	ds_read_b128 v[178:181], v242 offset:35840
	ds_read_b128 v[182:185], v242 offset:36864
	ds_read_b128 v[186:189], v242 offset:37888
	ds_read_b128 v[208:211], v242 offset:38912
	ds_read_b128 v[212:215], v242 offset:39936
	global_load_lds_dwordx4 v[216:217], off
	v_lshl_add_u64 v[216:217], s[40:41], 0, v[192:193]
	s_mov_b32 m0, s59
	s_nop 0
	global_load_lds_dwordx4 v[216:217], off
	s_waitcnt vmcnt(8)
	s_waitcnt lgkmcnt(0)
	s_setprio 1
	s_barrier
	v_mfma_f32_16x16x32_bf16 v[154:157], v[126:129], v[166:169], v[154:157]
	v_mfma_f32_16x16x32_bf16 v[150:153], v[134:137], v[166:169], v[150:153]
	v_mfma_f32_16x16x32_bf16 v[110:113], v[126:129], v[174:177], v[110:113]
	v_mfma_f32_16x16x32_bf16 v[106:109], v[134:137], v[174:177], v[106:109]
	v_mfma_f32_16x16x32_bf16 v[94:97], v[126:129], v[182:185], v[94:97]
	v_mfma_f32_16x16x32_bf16 v[90:93], v[134:137], v[182:185], v[90:93]
	v_mfma_f32_16x16x32_bf16 v[78:81], v[126:129], v[208:211], v[78:81]
	v_mfma_f32_16x16x32_bf16 v[74:77], v[134:137], v[208:211], v[74:77]
	v_mfma_f32_16x16x32_bf16 v[154:157], v[130:133], v[170:173], v[154:157]
	v_mfma_f32_16x16x32_bf16 v[150:153], v[138:141], v[170:173], v[150:153]
	v_mfma_f32_16x16x32_bf16 v[110:113], v[130:133], v[178:181], v[110:113]
	v_mfma_f32_16x16x32_bf16 v[106:109], v[138:141], v[178:181], v[106:109]
	v_mfma_f32_16x16x32_bf16 v[94:97], v[130:133], v[186:189], v[94:97]
	v_mfma_f32_16x16x32_bf16 v[90:93], v[138:141], v[186:189], v[90:93]
	v_mfma_f32_16x16x32_bf16 v[78:81], v[130:133], v[212:215], v[78:81]
	v_mfma_f32_16x16x32_bf16 v[74:77], v[138:141], v[212:215], v[74:77]
	v_mfma_f32_16x16x32_bf16 v[122:125], v[142:145], v[166:169], v[122:125]
	v_mfma_f32_16x16x32_bf16 v[114:117], v[158:161], v[166:169], v[114:117]
	v_mfma_f32_16x16x32_bf16 v[102:105], v[142:145], v[174:177], v[102:105]
	v_mfma_f32_16x16x32_bf16 v[98:101], v[158:161], v[174:177], v[98:101]
	v_mfma_f32_16x16x32_bf16 v[86:89], v[142:145], v[182:185], v[86:89]
	v_mfma_f32_16x16x32_bf16 v[82:85], v[158:161], v[182:185], v[82:85]
	v_mfma_f32_16x16x32_bf16 v[70:73], v[142:145], v[208:211], v[70:73]
	v_mfma_f32_16x16x32_bf16 v[66:69], v[158:161], v[208:211], v[66:69]
	v_mfma_f32_16x16x32_bf16 v[122:125], v[146:149], v[170:173], v[122:125]
	v_mfma_f32_16x16x32_bf16 v[114:117], v[162:165], v[170:173], v[114:117]
	v_mfma_f32_16x16x32_bf16 v[102:105], v[146:149], v[178:181], v[102:105]
	v_mfma_f32_16x16x32_bf16 v[98:101], v[162:165], v[178:181], v[98:101]
	v_mfma_f32_16x16x32_bf16 v[86:89], v[146:149], v[186:189], v[86:89]
	v_mfma_f32_16x16x32_bf16 v[82:85], v[162:165], v[186:189], v[82:85]
	v_mfma_f32_16x16x32_bf16 v[70:73], v[146:149], v[212:215], v[70:73]
	v_mfma_f32_16x16x32_bf16 v[66:69], v[162:165], v[212:215], v[66:69]
	s_barrier
	s_setprio 0
	s_add_i32 s4, s4, s51
	v_lshl_add_u64 v[194:195], v[194:195], 0, s[90:91]
	s_mov_b32 m0, s4
	ds_read_b128 v[166:169], v242 offset:49152
	ds_read_b128 v[170:173], v242 offset:50176
	ds_read_b128 v[174:177], v242 offset:51200
	ds_read_b128 v[178:181], v242 offset:52224
	ds_read_b128 v[182:185], v242 offset:53248
	ds_read_b128 v[186:189], v242 offset:54272
	ds_read_b128 v[208:211], v242 offset:55296
	ds_read_b128 v[212:215], v242 offset:56320
	global_load_lds_dwordx4 v[194:195], off
	s_add_i32 m0, s4, 0x2000
	s_add_u32 s38, s38, 0x40080
	v_lshl_add_u64 v[194:195], v[198:199], 0, s[90:91]
	s_addc_u32 s39, s39, 0
	s_add_i32 s4, s5, s51
	global_load_lds_dwordx4 v[194:195], off
	v_lshl_add_u64 v[194:195], s[38:39], 0, v[0:1]
	s_mov_b32 m0, s4
	s_nop 0
	global_load_lds_dwordx4 v[194:195], off
	v_lshl_add_u64 v[194:195], s[38:39], 0, v[190:191]
	s_add_i32 m0, s4, 0x2000
	s_nop 0
	global_load_lds_dwordx4 v[194:195], off
	v_lshl_add_u64 v[194:195], s[36:37], 0, v[202:203]
	s_mov_b32 m0, s68
	s_nop 0
	global_load_lds_dwordx4 v[194:195], off
	v_lshl_add_u64 v[194:195], s[36:37], 0, v[192:193]
	s_mov_b32 m0, s69
	s_nop 0
	global_load_lds_dwordx4 v[194:195], off
	s_waitcnt vmcnt(8)
	s_waitcnt lgkmcnt(0)
	s_setprio 1
	s_barrier
	v_mfma_f32_16x16x32_bf16 v[62:65], v[126:129], v[166:169], v[62:65]
	v_mfma_f32_16x16x32_bf16 v[58:61], v[134:137], v[166:169], v[58:61]
	v_mfma_f32_16x16x32_bf16 v[46:49], v[126:129], v[174:177], v[46:49]
	v_mfma_f32_16x16x32_bf16 v[42:45], v[134:137], v[174:177], v[42:45]
	v_mfma_f32_16x16x32_bf16 v[30:33], v[126:129], v[182:185], v[30:33]
	v_mfma_f32_16x16x32_bf16 v[26:29], v[134:137], v[182:185], v[26:29]
	v_mfma_f32_16x16x32_bf16 v[14:17], v[126:129], v[208:211], v[14:17]
	v_mfma_f32_16x16x32_bf16 v[10:13], v[134:137], v[208:211], v[10:13]
	v_mfma_f32_16x16x32_bf16 v[62:65], v[130:133], v[170:173], v[62:65]
	v_mfma_f32_16x16x32_bf16 v[58:61], v[138:141], v[170:173], v[58:61]
	v_mfma_f32_16x16x32_bf16 v[46:49], v[130:133], v[178:181], v[46:49]
	v_mfma_f32_16x16x32_bf16 v[42:45], v[138:141], v[178:181], v[42:45]
	v_mfma_f32_16x16x32_bf16 v[30:33], v[130:133], v[186:189], v[30:33]
	v_mfma_f32_16x16x32_bf16 v[26:29], v[138:141], v[186:189], v[26:29]
	v_mfma_f32_16x16x32_bf16 v[14:17], v[130:133], v[212:215], v[14:17]
	v_mfma_f32_16x16x32_bf16 v[10:13], v[138:141], v[212:215], v[10:13]
	v_mfma_f32_16x16x32_bf16 v[54:57], v[142:145], v[166:169], v[54:57]
	v_mfma_f32_16x16x32_bf16 v[50:53], v[158:161], v[166:169], v[50:53]
	v_mfma_f32_16x16x32_bf16 v[38:41], v[142:145], v[174:177], v[38:41]
	v_mfma_f32_16x16x32_bf16 v[34:37], v[158:161], v[174:177], v[34:37]
	v_mfma_f32_16x16x32_bf16 v[22:25], v[142:145], v[182:185], v[22:25]
	v_mfma_f32_16x16x32_bf16 v[18:21], v[158:161], v[182:185], v[18:21]
	v_mfma_f32_16x16x32_bf16 v[6:9], v[142:145], v[208:211], v[6:9]
	v_mfma_f32_16x16x32_bf16 v[2:5], v[158:161], v[208:211], v[2:5]
	v_mfma_f32_16x16x32_bf16 v[54:57], v[146:149], v[170:173], v[54:57]
	v_mfma_f32_16x16x32_bf16 v[50:53], v[162:165], v[170:173], v[50:53]
	v_mfma_f32_16x16x32_bf16 v[38:41], v[146:149], v[178:181], v[38:41]
	v_mfma_f32_16x16x32_bf16 v[34:37], v[162:165], v[178:181], v[34:37]
	v_mfma_f32_16x16x32_bf16 v[22:25], v[146:149], v[186:189], v[22:25]
	v_mfma_f32_16x16x32_bf16 v[18:21], v[162:165], v[186:189], v[18:21]
	v_mfma_f32_16x16x32_bf16 v[6:9], v[146:149], v[212:215], v[6:9]
	v_mfma_f32_16x16x32_bf16 v[2:5], v[162:165], v[212:215], v[2:5]
	s_barrier
	s_setprio 0
	s_add_i32 s86, s86, 2
	s_add_u32 s34, s34, 0x100
	s_addc_u32 s35, s35, 0
	s_cmp_gt_u32 s86, 13
	s_cbranch_scc0 .LBB0_773
	s_and_b64 vcc, exec, s[18:19]
	s_cbranch_vccz .LBB0_776
	s_barrier

.LBB0_861:
	s_add_u32 s4, s30, s34
	s_addc_u32 s5, s31, s35
	s_add_u32 s40, s4, 0x100
	s_addc_u32 s41, s5, 0
	s_add_u32 s38, s78, s34
	s_addc_u32 s39, s85, s35
	s_add_u32 s4, s4, 0x180
	s_addc_u32 s5, s5, 0
	s_add_i32 s65, 0, 0x10000
	s_add_i32 s87, 0, 0x14000
	v_add_u32_e32 v162, s65, v152
	v_add_u32_e32 v178, s87, v152
	ds_read_b128 v[146:149], v162
	ds_read_b128 v[154:157], v162 offset:1024
	ds_read_b128 v[158:161], v162 offset:2048
	ds_read_b128 v[162:165], v162 offset:3072
	ds_read_b128 v[166:169], v178
	ds_read_b128 v[170:173], v178 offset:1024
	ds_read_b128 v[174:177], v178 offset:2048
	ds_read_b128 v[178:181], v178 offset:3072
	s_cmpk_eq_i32 s34, 0x700
	s_cselect_b32 s37, s76, s5
	s_cselect_b32 s36, s75, s4
	s_cselect_b32 s39, s23, s39
	s_cselect_b32 s38, s74, s38
	s_cselect_b32 s41, s25, s41
	s_cselect_b32 s40, s73, s40
	v_lshl_add_u64 v[194:195], v[142:143], 0, s[34:35]
	s_add_i32 m0, s56, 0xc000
	ds_read_b128 v[182:185], v153
	ds_read_b128 v[186:189], v153 offset:1024
	ds_read_b128 v[190:193], v153 offset:2048
	ds_read_b128 v[202:205], v153 offset:3072
	ds_read_b128 v[206:209], v153 offset:4096
	ds_read_b128 v[210:213], v153 offset:5120
	ds_read_b128 v[214:217], v153 offset:6144
	ds_read_b128 v[218:221], v153 offset:7168
	global_load_lds_dwordx4 v[194:195], off
	v_lshl_add_u64 v[194:195], v[144:145], 0, s[34:35]
	s_add_i32 m0, s56, 0xe000
	s_nop 0
	global_load_lds_dwordx4 v[194:195], off
	s_waitcnt vmcnt(8)
	s_waitcnt lgkmcnt(0)
	s_setprio 1
	s_barrier
	v_mfma_f32_16x16x32_bf16 v[126:129], v[146:149], v[182:185], v[126:129]
	v_mfma_f32_16x16x32_bf16 v[122:125], v[158:161], v[182:185], v[122:125]
	v_mfma_f32_16x16x32_bf16 v[110:113], v[146:149], v[190:193], v[110:113]
	v_mfma_f32_16x16x32_bf16 v[106:109], v[158:161], v[190:193], v[106:109]
	v_mfma_f32_16x16x32_bf16 v[94:97], v[146:149], v[206:209], v[94:97]
	v_mfma_f32_16x16x32_bf16 v[90:93], v[158:161], v[206:209], v[90:93]
	v_mfma_f32_16x16x32_bf16 v[78:81], v[146:149], v[214:217], v[78:81]
	v_mfma_f32_16x16x32_bf16 v[74:77], v[158:161], v[214:217], v[74:77]
	v_mfma_f32_16x16x32_bf16 v[126:129], v[154:157], v[186:189], v[126:129]
	v_mfma_f32_16x16x32_bf16 v[122:125], v[162:165], v[186:189], v[122:125]
	v_mfma_f32_16x16x32_bf16 v[110:113], v[154:157], v[202:205], v[110:113]
	v_mfma_f32_16x16x32_bf16 v[106:109], v[162:165], v[202:205], v[106:109]
	v_mfma_f32_16x16x32_bf16 v[94:97], v[154:157], v[210:213], v[94:97]
	v_mfma_f32_16x16x32_bf16 v[90:93], v[162:165], v[210:213], v[90:93]
	v_mfma_f32_16x16x32_bf16 v[78:81], v[154:157], v[218:221], v[78:81]
	v_mfma_f32_16x16x32_bf16 v[74:77], v[162:165], v[218:221], v[74:77]
	v_mfma_f32_16x16x32_bf16 v[118:121], v[166:169], v[182:185], v[118:121]
	v_mfma_f32_16x16x32_bf16 v[114:117], v[174:177], v[182:185], v[114:117]
	v_mfma_f32_16x16x32_bf16 v[102:105], v[166:169], v[190:193], v[102:105]
	v_mfma_f32_16x16x32_bf16 v[98:101], v[174:177], v[190:193], v[98:101]
	v_mfma_f32_16x16x32_bf16 v[86:89], v[166:169], v[206:209], v[86:89]
	v_mfma_f32_16x16x32_bf16 v[82:85], v[174:177], v[206:209], v[82:85]
	v_mfma_f32_16x16x32_bf16 v[70:73], v[166:169], v[214:217], v[70:73]
	v_mfma_f32_16x16x32_bf16 v[66:69], v[174:177], v[214:217], v[66:69]
	v_mfma_f32_16x16x32_bf16 v[118:121], v[170:173], v[186:189], v[118:121]
	v_mfma_f32_16x16x32_bf16 v[114:117], v[178:181], v[186:189], v[114:117]
	v_mfma_f32_16x16x32_bf16 v[102:105], v[170:173], v[202:205], v[102:105]
	v_mfma_f32_16x16x32_bf16 v[98:101], v[178:181], v[202:205], v[98:101]
	v_mfma_f32_16x16x32_bf16 v[86:89], v[170:173], v[210:213], v[86:89]
	v_mfma_f32_16x16x32_bf16 v[82:85], v[178:181], v[210:213], v[82:85]
	v_mfma_f32_16x16x32_bf16 v[70:73], v[170:173], v[218:221], v[70:73]
	v_mfma_f32_16x16x32_bf16 v[66:69], v[178:181], v[218:221], v[66:69]
	s_barrier
	s_setprio 0
	s_add_i32 s4, s65, s51
	v_lshl_add_u64 v[194:195], s[38:39], 0, v[134:135]
	s_mov_b32 m0, s4
	ds_read_b128 v[182:185], v153 offset:16384
	ds_read_b128 v[186:189], v153 offset:17408
	ds_read_b128 v[190:193], v153 offset:18432
	ds_read_b128 v[202:205], v153 offset:19456
	ds_read_b128 v[206:209], v153 offset:20480
	ds_read_b128 v[210:213], v153 offset:21504
	ds_read_b128 v[214:217], v153 offset:22528
	ds_read_b128 v[218:221], v153 offset:23552
	global_load_lds_dwordx4 v[194:195], off
	s_add_i32 m0, s4, 0x2000
	s_add_u32 vcc_lo, s38, 0x40000
	v_lshl_add_u64 v[198:199], s[38:39], 0, v[130:131]
	s_addc_u32 vcc_hi, s39, 0
	s_add_i32 s4, s87, s51
	global_load_lds_dwordx4 v[198:199], off
	v_lshl_add_u64 v[222:223], vcc, 0, v[134:135]
	s_mov_b32 m0, s4
	s_nop 0
	global_load_lds_dwordx4 v[222:223], off
	v_lshl_add_u64 v[222:223], vcc, 0, v[130:131]
	s_add_i32 m0, s4, 0x2000
	s_nop 0
	global_load_lds_dwordx4 v[222:223], off
	v_lshl_add_u64 v[222:223], s[40:41], 0, v[136:137]
	s_mov_b32 m0, s56
	s_nop 0
	global_load_lds_dwordx4 v[222:223], off
	v_lshl_add_u64 v[222:223], s[40:41], 0, v[132:133]
	s_mov_b32 m0, s57
	s_nop 0
	global_load_lds_dwordx4 v[222:223], off
	s_waitcnt vmcnt(8)
	s_waitcnt lgkmcnt(0)
	s_setprio 1
	s_barrier
	v_mfma_f32_16x16x32_bf16 v[62:65], v[146:149], v[182:185], v[62:65]
	v_mfma_f32_16x16x32_bf16 v[58:61], v[158:161], v[182:185], v[58:61]
	v_mfma_f32_16x16x32_bf16 v[46:49], v[146:149], v[190:193], v[46:49]
	v_mfma_f32_16x16x32_bf16 v[42:45], v[158:161], v[190:193], v[42:45]
	v_mfma_f32_16x16x32_bf16 v[30:33], v[146:149], v[206:209], v[30:33]
	v_mfma_f32_16x16x32_bf16 v[26:29], v[158:161], v[206:209], v[26:29]
	v_mfma_f32_16x16x32_bf16 v[14:17], v[146:149], v[214:217], v[14:17]
	v_mfma_f32_16x16x32_bf16 v[10:13], v[158:161], v[214:217], v[10:13]
	v_mfma_f32_16x16x32_bf16 v[62:65], v[154:157], v[186:189], v[62:65]
	v_mfma_f32_16x16x32_bf16 v[58:61], v[162:165], v[186:189], v[58:61]
	v_mfma_f32_16x16x32_bf16 v[46:49], v[154:157], v[202:205], v[46:49]
	v_mfma_f32_16x16x32_bf16 v[42:45], v[162:165], v[202:205], v[42:45]
	v_mfma_f32_16x16x32_bf16 v[30:33], v[154:157], v[210:213], v[30:33]
	v_mfma_f32_16x16x32_bf16 v[26:29], v[162:165], v[210:213], v[26:29]
	v_mfma_f32_16x16x32_bf16 v[14:17], v[154:157], v[218:221], v[14:17]
	v_mfma_f32_16x16x32_bf16 v[10:13], v[162:165], v[218:221], v[10:13]
	v_mfma_f32_16x16x32_bf16 v[54:57], v[166:169], v[182:185], v[54:57]
	v_mfma_f32_16x16x32_bf16 v[50:53], v[174:177], v[182:185], v[50:53]
	v_mfma_f32_16x16x32_bf16 v[38:41], v[166:169], v[190:193], v[38:41]
	v_mfma_f32_16x16x32_bf16 v[34:37], v[174:177], v[190:193], v[34:37]
	v_mfma_f32_16x16x32_bf16 v[22:25], v[166:169], v[206:209], v[22:25]
	v_mfma_f32_16x16x32_bf16 v[18:21], v[174:177], v[206:209], v[18:21]
	v_mfma_f32_16x16x32_bf16 v[6:9], v[166:169], v[214:217], v[6:9]
	v_mfma_f32_16x16x32_bf16 v[2:5], v[174:177], v[214:217], v[2:5]
	v_mfma_f32_16x16x32_bf16 v[54:57], v[170:173], v[186:189], v[54:57]
	v_mfma_f32_16x16x32_bf16 v[50:53], v[178:181], v[186:189], v[50:53]
	v_mfma_f32_16x16x32_bf16 v[38:41], v[170:173], v[202:205], v[38:41]
	v_mfma_f32_16x16x32_bf16 v[34:37], v[178:181], v[202:205], v[34:37]
	v_mfma_f32_16x16x32_bf16 v[22:25], v[170:173], v[210:213], v[22:25]
	v_mfma_f32_16x16x32_bf16 v[18:21], v[178:181], v[210:213], v[18:21]
	v_mfma_f32_16x16x32_bf16 v[6:9], v[170:173], v[218:221], v[6:9]
	v_mfma_f32_16x16x32_bf16 v[2:5], v[178:181], v[218:221], v[2:5]
	s_barrier
	s_setprio 0
	s_add_i32 s4, 0, 0x18000
	s_add_i32 s5, 0, 0x1c000
	v_add_u32_e32 v162, s4, v152
	v_add_u32_e32 v178, s5, v152
	ds_read_b128 v[146:149], v162
	ds_read_b128 v[154:157], v162 offset:1024
	ds_read_b128 v[158:161], v162 offset:2048
	ds_read_b128 v[162:165], v162 offset:3072
	ds_read_b128 v[166:169], v178
	ds_read_b128 v[170:173], v178 offset:1024
	ds_read_b128 v[174:177], v178 offset:2048
	ds_read_b128 v[178:181], v178 offset:3072
	s_add_u32 s40, s40, 0x40000
	s_addc_u32 s41, s41, 0
	s_mov_b32 m0, s58
	v_lshl_add_u64 v[222:223], s[40:41], 0, v[136:137]
	ds_read_b128 v[182:185], v153 offset:32768
	ds_read_b128 v[186:189], v153 offset:33792
	ds_read_b128 v[190:193], v153 offset:34816
	ds_read_b128 v[202:205], v153 offset:35840
	ds_read_b128 v[206:209], v153 offset:36864
	ds_read_b128 v[210:213], v153 offset:37888
	ds_read_b128 v[214:217], v153 offset:38912
	ds_read_b128 v[218:221], v153 offset:39936
	global_load_lds_dwordx4 v[222:223], off
	v_lshl_add_u64 v[222:223], s[40:41], 0, v[132:133]
	s_mov_b32 m0, s59
	s_nop 0
	global_load_lds_dwordx4 v[222:223], off
	s_waitcnt vmcnt(8)
	s_waitcnt lgkmcnt(0)
	s_setprio 1
	s_barrier
	v_mfma_f32_16x16x32_bf16 v[126:129], v[146:149], v[182:185], v[126:129]
	v_mfma_f32_16x16x32_bf16 v[122:125], v[158:161], v[182:185], v[122:125]
	v_mfma_f32_16x16x32_bf16 v[110:113], v[146:149], v[190:193], v[110:113]
	v_mfma_f32_16x16x32_bf16 v[106:109], v[158:161], v[190:193], v[106:109]
	v_mfma_f32_16x16x32_bf16 v[94:97], v[146:149], v[206:209], v[94:97]
	v_mfma_f32_16x16x32_bf16 v[90:93], v[158:161], v[206:209], v[90:93]
	v_mfma_f32_16x16x32_bf16 v[78:81], v[146:149], v[214:217], v[78:81]
	v_mfma_f32_16x16x32_bf16 v[74:77], v[158:161], v[214:217], v[74:77]
	v_mfma_f32_16x16x32_bf16 v[126:129], v[154:157], v[186:189], v[126:129]
	v_mfma_f32_16x16x32_bf16 v[122:125], v[162:165], v[186:189], v[122:125]
	v_mfma_f32_16x16x32_bf16 v[110:113], v[154:157], v[202:205], v[110:113]
	v_mfma_f32_16x16x32_bf16 v[106:109], v[162:165], v[202:205], v[106:109]
	v_mfma_f32_16x16x32_bf16 v[94:97], v[154:157], v[210:213], v[94:97]
	v_mfma_f32_16x16x32_bf16 v[90:93], v[162:165], v[210:213], v[90:93]
	v_mfma_f32_16x16x32_bf16 v[78:81], v[154:157], v[218:221], v[78:81]
	v_mfma_f32_16x16x32_bf16 v[74:77], v[162:165], v[218:221], v[74:77]
	v_mfma_f32_16x16x32_bf16 v[118:121], v[166:169], v[182:185], v[118:121]
	v_mfma_f32_16x16x32_bf16 v[114:117], v[174:177], v[182:185], v[114:117]
	v_mfma_f32_16x16x32_bf16 v[102:105], v[166:169], v[190:193], v[102:105]
	v_mfma_f32_16x16x32_bf16 v[98:101], v[174:177], v[190:193], v[98:101]
	v_mfma_f32_16x16x32_bf16 v[86:89], v[166:169], v[206:209], v[86:89]
	v_mfma_f32_16x16x32_bf16 v[82:85], v[174:177], v[206:209], v[82:85]
	v_mfma_f32_16x16x32_bf16 v[70:73], v[166:169], v[214:217], v[70:73]
	v_mfma_f32_16x16x32_bf16 v[66:69], v[174:177], v[214:217], v[66:69]
	v_mfma_f32_16x16x32_bf16 v[118:121], v[170:173], v[186:189], v[118:121]
	v_mfma_f32_16x16x32_bf16 v[114:117], v[178:181], v[186:189], v[114:117]
	v_mfma_f32_16x16x32_bf16 v[102:105], v[170:173], v[202:205], v[102:105]
	v_mfma_f32_16x16x32_bf16 v[98:101], v[178:181], v[202:205], v[98:101]
	v_mfma_f32_16x16x32_bf16 v[86:89], v[170:173], v[210:213], v[86:89]
	v_mfma_f32_16x16x32_bf16 v[82:85], v[178:181], v[210:213], v[82:85]
	v_mfma_f32_16x16x32_bf16 v[70:73], v[170:173], v[218:221], v[70:73]
	v_mfma_f32_16x16x32_bf16 v[66:69], v[178:181], v[218:221], v[66:69]
	s_barrier
	s_setprio 0
	s_add_i32 s4, s4, s51
	v_lshl_add_u64 v[194:195], v[194:195], 0, s[90:91]
	s_mov_b32 m0, s4
	ds_read_b128 v[182:185], v153 offset:49152
	ds_read_b128 v[186:189], v153 offset:50176
	ds_read_b128 v[190:193], v153 offset:51200
	ds_read_b128 v[202:205], v153 offset:52224
	ds_read_b128 v[206:209], v153 offset:53248
	ds_read_b128 v[210:213], v153 offset:54272
	ds_read_b128 v[214:217], v153 offset:55296
	ds_read_b128 v[218:221], v153 offset:56320
	global_load_lds_dwordx4 v[194:195], off
	s_add_i32 m0, s4, 0x2000
	s_add_u32 s38, s38, 0x40080
	v_lshl_add_u64 v[194:195], v[198:199], 0, s[90:91]
	s_addc_u32 s39, s39, 0
	s_add_i32 s4, s5, s51
	global_load_lds_dwordx4 v[194:195], off
	v_lshl_add_u64 v[194:195], s[38:39], 0, v[134:135]
	s_mov_b32 m0, s4
	s_nop 0
	global_load_lds_dwordx4 v[194:195], off
	v_lshl_add_u64 v[194:195], s[38:39], 0, v[130:131]
	s_add_i32 m0, s4, 0x2000
	s_nop 0
	global_load_lds_dwordx4 v[194:195], off
	v_lshl_add_u64 v[194:195], s[36:37], 0, v[136:137]
	s_mov_b32 m0, s68
	s_nop 0
	global_load_lds_dwordx4 v[194:195], off
	v_lshl_add_u64 v[194:195], s[36:37], 0, v[132:133]
	s_mov_b32 m0, s69
	s_nop 0
	global_load_lds_dwordx4 v[194:195], off
	s_waitcnt vmcnt(8)
	s_waitcnt lgkmcnt(0)
	s_setprio 1
	s_barrier
	v_mfma_f32_16x16x32_bf16 v[62:65], v[146:149], v[182:185], v[62:65]
	v_mfma_f32_16x16x32_bf16 v[58:61], v[158:161], v[182:185], v[58:61]
	v_mfma_f32_16x16x32_bf16 v[46:49], v[146:149], v[190:193], v[46:49]
	v_mfma_f32_16x16x32_bf16 v[42:45], v[158:161], v[190:193], v[42:45]
	v_mfma_f32_16x16x32_bf16 v[30:33], v[146:149], v[206:209], v[30:33]
	v_mfma_f32_16x16x32_bf16 v[26:29], v[158:161], v[206:209], v[26:29]
	v_mfma_f32_16x16x32_bf16 v[14:17], v[146:149], v[214:217], v[14:17]
	v_mfma_f32_16x16x32_bf16 v[10:13], v[158:161], v[214:217], v[10:13]
	v_mfma_f32_16x16x32_bf16 v[62:65], v[154:157], v[186:189], v[62:65]
	v_mfma_f32_16x16x32_bf16 v[58:61], v[162:165], v[186:189], v[58:61]
	v_mfma_f32_16x16x32_bf16 v[46:49], v[154:157], v[202:205], v[46:49]
	v_mfma_f32_16x16x32_bf16 v[42:45], v[162:165], v[202:205], v[42:45]
	v_mfma_f32_16x16x32_bf16 v[30:33], v[154:157], v[210:213], v[30:33]
	v_mfma_f32_16x16x32_bf16 v[26:29], v[162:165], v[210:213], v[26:29]
	v_mfma_f32_16x16x32_bf16 v[14:17], v[154:157], v[218:221], v[14:17]
	v_mfma_f32_16x16x32_bf16 v[10:13], v[162:165], v[218:221], v[10:13]
	v_mfma_f32_16x16x32_bf16 v[54:57], v[166:169], v[182:185], v[54:57]
	v_mfma_f32_16x16x32_bf16 v[50:53], v[174:177], v[182:185], v[50:53]
	v_mfma_f32_16x16x32_bf16 v[38:41], v[166:169], v[190:193], v[38:41]
	v_mfma_f32_16x16x32_bf16 v[34:37], v[174:177], v[190:193], v[34:37]
	v_mfma_f32_16x16x32_bf16 v[22:25], v[166:169], v[206:209], v[22:25]
	v_mfma_f32_16x16x32_bf16 v[18:21], v[174:177], v[206:209], v[18:21]
	v_mfma_f32_16x16x32_bf16 v[6:9], v[166:169], v[214:217], v[6:9]
	v_mfma_f32_16x16x32_bf16 v[2:5], v[174:177], v[214:217], v[2:5]
	v_mfma_f32_16x16x32_bf16 v[54:57], v[170:173], v[186:189], v[54:57]
	v_mfma_f32_16x16x32_bf16 v[50:53], v[178:181], v[186:189], v[50:53]
	v_mfma_f32_16x16x32_bf16 v[38:41], v[170:173], v[202:205], v[38:41]
	v_mfma_f32_16x16x32_bf16 v[34:37], v[178:181], v[202:205], v[34:37]
	v_mfma_f32_16x16x32_bf16 v[22:25], v[170:173], v[210:213], v[22:25]
	v_mfma_f32_16x16x32_bf16 v[18:21], v[178:181], v[210:213], v[18:21]
	v_mfma_f32_16x16x32_bf16 v[6:9], v[170:173], v[218:221], v[6:9]
	v_mfma_f32_16x16x32_bf16 v[2:5], v[178:181], v[218:221], v[2:5]
	s_barrier
	s_setprio 0
	s_add_i32 s86, s86, 2
	s_add_u32 s34, s34, 0x100
	s_addc_u32 s35, s35, 0
	s_cmp_gt_u32 s86, 13
	s_cbranch_scc0 .LBB0_861
	s_and_b64 vcc, exec, s[20:21]
	s_cbranch_vccz .LBB0_864
	s_barrier

.LBB0_915:
	s_add_u32 s4, s34, s36
	s_addc_u32 s5, s35, s37
	s_add_u32 s42, s4, 0x100
	s_addc_u32 s43, s5, 0
	s_add_u32 s40, s76, s36
	s_addc_u32 s41, s78, s37
	s_add_u32 s4, s4, 0x180
	s_addc_u32 s5, s5, 0
	s_add_i32 s85, 0, 0x10000
	s_add_i32 vcc_lo, 0, 0x14000
	v_add_u32_e32 v138, s85, v231
	v_add_u32_e32 v162, vcc_lo, v231
	ds_read_b128 v[126:129], v138
	ds_read_b128 v[130:133], v138 offset:1024
	ds_read_b128 v[134:137], v138 offset:2048
	ds_read_b128 v[138:141], v138 offset:3072
	ds_read_b128 v[142:145], v162
	ds_read_b128 v[146:149], v162 offset:1024
	ds_read_b128 v[158:161], v162 offset:2048
	ds_read_b128 v[162:165], v162 offset:3072
	s_cmpk_eq_i32 s36, 0x1f00
	s_cselect_b32 s39, s75, s5
	s_cselect_b32 s38, s74, s4
	s_cselect_b32 s41, s25, s41
	s_cselect_b32 s40, s73, s40
	s_cselect_b32 s43, s27, s43
	s_cselect_b32 s42, s72, s42
	v_lshl_add_u64 v[194:195], v[118:119], 0, s[36:37]
	s_add_i32 m0, s58, 0xc000
	ds_read_b128 v[166:169], v242
	ds_read_b128 v[170:173], v242 offset:1024
	ds_read_b128 v[174:177], v242 offset:2048
	ds_read_b128 v[178:181], v242 offset:3072
	ds_read_b128 v[182:185], v242 offset:4096
	ds_read_b128 v[186:189], v242 offset:5120
	ds_read_b128 v[208:211], v242 offset:6144
	ds_read_b128 v[212:215], v242 offset:7168
	global_load_lds_dwordx4 v[194:195], off
	v_lshl_add_u64 v[194:195], v[120:121], 0, s[36:37]
	s_add_i32 m0, s58, 0xe000
	s_nop 0
	global_load_lds_dwordx4 v[194:195], off
	s_waitcnt vmcnt(8)
	s_waitcnt lgkmcnt(0)
	s_setprio 1
	s_barrier
	v_mfma_f32_16x16x32_bf16 v[154:157], v[126:129], v[166:169], v[154:157]
	v_mfma_f32_16x16x32_bf16 v[150:153], v[134:137], v[166:169], v[150:153]
	v_mfma_f32_16x16x32_bf16 v[110:113], v[126:129], v[174:177], v[110:113]
	v_mfma_f32_16x16x32_bf16 v[106:109], v[134:137], v[174:177], v[106:109]
	v_mfma_f32_16x16x32_bf16 v[94:97], v[126:129], v[182:185], v[94:97]
	v_mfma_f32_16x16x32_bf16 v[90:93], v[134:137], v[182:185], v[90:93]
	v_mfma_f32_16x16x32_bf16 v[78:81], v[126:129], v[208:211], v[78:81]
	v_mfma_f32_16x16x32_bf16 v[74:77], v[134:137], v[208:211], v[74:77]
	v_mfma_f32_16x16x32_bf16 v[154:157], v[130:133], v[170:173], v[154:157]
	v_mfma_f32_16x16x32_bf16 v[150:153], v[138:141], v[170:173], v[150:153]
	v_mfma_f32_16x16x32_bf16 v[110:113], v[130:133], v[178:181], v[110:113]
	v_mfma_f32_16x16x32_bf16 v[106:109], v[138:141], v[178:181], v[106:109]
	v_mfma_f32_16x16x32_bf16 v[94:97], v[130:133], v[186:189], v[94:97]
	v_mfma_f32_16x16x32_bf16 v[90:93], v[138:141], v[186:189], v[90:93]
	v_mfma_f32_16x16x32_bf16 v[78:81], v[130:133], v[212:215], v[78:81]
	v_mfma_f32_16x16x32_bf16 v[74:77], v[138:141], v[212:215], v[74:77]
	v_mfma_f32_16x16x32_bf16 v[122:125], v[142:145], v[166:169], v[122:125]
	v_mfma_f32_16x16x32_bf16 v[114:117], v[158:161], v[166:169], v[114:117]
	v_mfma_f32_16x16x32_bf16 v[102:105], v[142:145], v[174:177], v[102:105]
	v_mfma_f32_16x16x32_bf16 v[98:101], v[158:161], v[174:177], v[98:101]
	v_mfma_f32_16x16x32_bf16 v[86:89], v[142:145], v[182:185], v[86:89]
	v_mfma_f32_16x16x32_bf16 v[82:85], v[158:161], v[182:185], v[82:85]
	v_mfma_f32_16x16x32_bf16 v[70:73], v[142:145], v[208:211], v[70:73]
	v_mfma_f32_16x16x32_bf16 v[66:69], v[158:161], v[208:211], v[66:69]
	v_mfma_f32_16x16x32_bf16 v[122:125], v[146:149], v[170:173], v[122:125]
	v_mfma_f32_16x16x32_bf16 v[114:117], v[162:165], v[170:173], v[114:117]
	v_mfma_f32_16x16x32_bf16 v[102:105], v[146:149], v[178:181], v[102:105]
	v_mfma_f32_16x16x32_bf16 v[98:101], v[162:165], v[178:181], v[98:101]
	v_mfma_f32_16x16x32_bf16 v[86:89], v[146:149], v[186:189], v[86:89]
	v_mfma_f32_16x16x32_bf16 v[82:85], v[162:165], v[186:189], v[82:85]
	v_mfma_f32_16x16x32_bf16 v[70:73], v[146:149], v[212:215], v[70:73]
	v_mfma_f32_16x16x32_bf16 v[66:69], v[162:165], v[212:215], v[66:69]
	s_barrier
	s_setprio 0
	s_add_i32 s4, s85, s57
	v_lshl_add_u64 v[194:195], s[40:41], 0, v[0:1]
	s_mov_b32 m0, s4
	ds_read_b128 v[166:169], v242 offset:16384
	ds_read_b128 v[170:173], v242 offset:17408
	ds_read_b128 v[174:177], v242 offset:18432
	ds_read_b128 v[178:181], v242 offset:19456
	ds_read_b128 v[182:185], v242 offset:20480
	ds_read_b128 v[186:189], v242 offset:21504
	ds_read_b128 v[208:211], v242 offset:22528
	ds_read_b128 v[212:215], v242 offset:23552
	global_load_lds_dwordx4 v[194:195], off
	s_add_i32 m0, s4, 0x2000
	s_add_u32 s86, s40, 0x100000
	v_lshl_add_u64 v[198:199], s[40:41], 0, v[190:191]
	s_addc_u32 s87, s41, 0
	s_add_i32 s4, vcc_lo, s57
	global_load_lds_dwordx4 v[198:199], off
	v_lshl_add_u64 v[216:217], s[86:87], 0, v[0:1]
	s_mov_b32 m0, s4
	s_nop 0
	global_load_lds_dwordx4 v[216:217], off
	v_lshl_add_u64 v[216:217], s[86:87], 0, v[190:191]
	s_add_i32 m0, s4, 0x2000
	s_nop 0
	global_load_lds_dwordx4 v[216:217], off
	v_lshl_add_u64 v[216:217], s[42:43], 0, v[202:203]
	s_mov_b32 m0, s58
	s_nop 0
	global_load_lds_dwordx4 v[216:217], off
	v_lshl_add_u64 v[216:217], s[42:43], 0, v[192:193]
	s_mov_b32 m0, s59
	s_nop 0
	global_load_lds_dwordx4 v[216:217], off
	s_waitcnt vmcnt(8)
	s_waitcnt lgkmcnt(0)
	s_setprio 1
	s_barrier
	v_mfma_f32_16x16x32_bf16 v[62:65], v[126:129], v[166:169], v[62:65]
	v_mfma_f32_16x16x32_bf16 v[58:61], v[134:137], v[166:169], v[58:61]
	v_mfma_f32_16x16x32_bf16 v[46:49], v[126:129], v[174:177], v[46:49]
	v_mfma_f32_16x16x32_bf16 v[42:45], v[134:137], v[174:177], v[42:45]
	v_mfma_f32_16x16x32_bf16 v[30:33], v[126:129], v[182:185], v[30:33]
	v_mfma_f32_16x16x32_bf16 v[26:29], v[134:137], v[182:185], v[26:29]
	v_mfma_f32_16x16x32_bf16 v[14:17], v[126:129], v[208:211], v[14:17]
	v_mfma_f32_16x16x32_bf16 v[10:13], v[134:137], v[208:211], v[10:13]
	v_mfma_f32_16x16x32_bf16 v[62:65], v[130:133], v[170:173], v[62:65]
	v_mfma_f32_16x16x32_bf16 v[58:61], v[138:141], v[170:173], v[58:61]
	v_mfma_f32_16x16x32_bf16 v[46:49], v[130:133], v[178:181], v[46:49]
	v_mfma_f32_16x16x32_bf16 v[42:45], v[138:141], v[178:181], v[42:45]
	v_mfma_f32_16x16x32_bf16 v[30:33], v[130:133], v[186:189], v[30:33]
	v_mfma_f32_16x16x32_bf16 v[26:29], v[138:141], v[186:189], v[26:29]
	v_mfma_f32_16x16x32_bf16 v[14:17], v[130:133], v[212:215], v[14:17]
	v_mfma_f32_16x16x32_bf16 v[10:13], v[138:141], v[212:215], v[10:13]
	v_mfma_f32_16x16x32_bf16 v[54:57], v[142:145], v[166:169], v[54:57]
	v_mfma_f32_16x16x32_bf16 v[50:53], v[158:161], v[166:169], v[50:53]
	v_mfma_f32_16x16x32_bf16 v[38:41], v[142:145], v[174:177], v[38:41]
	v_mfma_f32_16x16x32_bf16 v[34:37], v[158:161], v[174:177], v[34:37]
	v_mfma_f32_16x16x32_bf16 v[22:25], v[142:145], v[182:185], v[22:25]
	v_mfma_f32_16x16x32_bf16 v[18:21], v[158:161], v[182:185], v[18:21]
	v_mfma_f32_16x16x32_bf16 v[6:9], v[142:145], v[208:211], v[6:9]
	v_mfma_f32_16x16x32_bf16 v[2:5], v[158:161], v[208:211], v[2:5]
	v_mfma_f32_16x16x32_bf16 v[54:57], v[146:149], v[170:173], v[54:57]
	v_mfma_f32_16x16x32_bf16 v[50:53], v[162:165], v[170:173], v[50:53]
	v_mfma_f32_16x16x32_bf16 v[38:41], v[146:149], v[178:181], v[38:41]
	v_mfma_f32_16x16x32_bf16 v[34:37], v[162:165], v[178:181], v[34:37]
	v_mfma_f32_16x16x32_bf16 v[22:25], v[146:149], v[186:189], v[22:25]
	v_mfma_f32_16x16x32_bf16 v[18:21], v[162:165], v[186:189], v[18:21]
	v_mfma_f32_16x16x32_bf16 v[6:9], v[146:149], v[212:215], v[6:9]
	v_mfma_f32_16x16x32_bf16 v[2:5], v[162:165], v[212:215], v[2:5]
	s_barrier
	s_setprio 0
	s_add_i32 s4, 0, 0x18000
	s_add_i32 s5, 0, 0x1c000
	v_add_u32_e32 v138, s4, v231
	v_add_u32_e32 v162, s5, v231
	ds_read_b128 v[126:129], v138
	ds_read_b128 v[130:133], v138 offset:1024
	ds_read_b128 v[134:137], v138 offset:2048
	ds_read_b128 v[138:141], v138 offset:3072
	ds_read_b128 v[142:145], v162
	ds_read_b128 v[146:149], v162 offset:1024
	ds_read_b128 v[158:161], v162 offset:2048
	ds_read_b128 v[162:165], v162 offset:3072
	s_add_u32 s42, s42, 0x100000
	s_addc_u32 s43, s43, 0
	s_mov_b32 m0, s65
	v_lshl_add_u64 v[216:217], s[42:43], 0, v[202:203]
	ds_read_b128 v[166:169], v242 offset:32768
	ds_read_b128 v[170:173], v242 offset:33792
	ds_read_b128 v[174:177], v242 offset:34816
	ds_read_b128 v[178:181], v242 offset:35840
	ds_read_b128 v[182:185], v242 offset:36864
	ds_read_b128 v[186:189], v242 offset:37888
	ds_read_b128 v[208:211], v242 offset:38912
	ds_read_b128 v[212:215], v242 offset:39936
	global_load_lds_dwordx4 v[216:217], off
	v_lshl_add_u64 v[216:217], s[42:43], 0, v[192:193]
	s_mov_b32 m0, s68
	s_nop 0
	global_load_lds_dwordx4 v[216:217], off
	s_waitcnt vmcnt(8)
	s_waitcnt lgkmcnt(0)
	s_setprio 1
	s_barrier
	v_mfma_f32_16x16x32_bf16 v[154:157], v[126:129], v[166:169], v[154:157]
	v_mfma_f32_16x16x32_bf16 v[150:153], v[134:137], v[166:169], v[150:153]
	v_mfma_f32_16x16x32_bf16 v[110:113], v[126:129], v[174:177], v[110:113]
	v_mfma_f32_16x16x32_bf16 v[106:109], v[134:137], v[174:177], v[106:109]
	v_mfma_f32_16x16x32_bf16 v[94:97], v[126:129], v[182:185], v[94:97]
	v_mfma_f32_16x16x32_bf16 v[90:93], v[134:137], v[182:185], v[90:93]
	v_mfma_f32_16x16x32_bf16 v[78:81], v[126:129], v[208:211], v[78:81]
	v_mfma_f32_16x16x32_bf16 v[74:77], v[134:137], v[208:211], v[74:77]
	v_mfma_f32_16x16x32_bf16 v[154:157], v[130:133], v[170:173], v[154:157]
	v_mfma_f32_16x16x32_bf16 v[150:153], v[138:141], v[170:173], v[150:153]
	v_mfma_f32_16x16x32_bf16 v[110:113], v[130:133], v[178:181], v[110:113]
	v_mfma_f32_16x16x32_bf16 v[106:109], v[138:141], v[178:181], v[106:109]
	v_mfma_f32_16x16x32_bf16 v[94:97], v[130:133], v[186:189], v[94:97]
	v_mfma_f32_16x16x32_bf16 v[90:93], v[138:141], v[186:189], v[90:93]
	v_mfma_f32_16x16x32_bf16 v[78:81], v[130:133], v[212:215], v[78:81]
	v_mfma_f32_16x16x32_bf16 v[74:77], v[138:141], v[212:215], v[74:77]
	v_mfma_f32_16x16x32_bf16 v[122:125], v[142:145], v[166:169], v[122:125]
	v_mfma_f32_16x16x32_bf16 v[114:117], v[158:161], v[166:169], v[114:117]
	v_mfma_f32_16x16x32_bf16 v[102:105], v[142:145], v[174:177], v[102:105]
	v_mfma_f32_16x16x32_bf16 v[98:101], v[158:161], v[174:177], v[98:101]
	v_mfma_f32_16x16x32_bf16 v[86:89], v[142:145], v[182:185], v[86:89]
	v_mfma_f32_16x16x32_bf16 v[82:85], v[158:161], v[182:185], v[82:85]
	v_mfma_f32_16x16x32_bf16 v[70:73], v[142:145], v[208:211], v[70:73]
	v_mfma_f32_16x16x32_bf16 v[66:69], v[158:161], v[208:211], v[66:69]
	v_mfma_f32_16x16x32_bf16 v[122:125], v[146:149], v[170:173], v[122:125]
	v_mfma_f32_16x16x32_bf16 v[114:117], v[162:165], v[170:173], v[114:117]
	v_mfma_f32_16x16x32_bf16 v[102:105], v[146:149], v[178:181], v[102:105]
	v_mfma_f32_16x16x32_bf16 v[98:101], v[162:165], v[178:181], v[98:101]
	v_mfma_f32_16x16x32_bf16 v[86:89], v[146:149], v[186:189], v[86:89]
	v_mfma_f32_16x16x32_bf16 v[82:85], v[162:165], v[186:189], v[82:85]
	v_mfma_f32_16x16x32_bf16 v[70:73], v[146:149], v[212:215], v[70:73]
	v_mfma_f32_16x16x32_bf16 v[66:69], v[162:165], v[212:215], v[66:69]
	s_barrier
	s_setprio 0
	s_add_i32 s4, s4, s57
	v_lshl_add_u64 v[194:195], v[194:195], 0, s[90:91]
	s_mov_b32 m0, s4
	ds_read_b128 v[166:169], v242 offset:49152
	ds_read_b128 v[170:173], v242 offset:50176
	ds_read_b128 v[174:177], v242 offset:51200
	ds_read_b128 v[178:181], v242 offset:52224
	ds_read_b128 v[182:185], v242 offset:53248
	ds_read_b128 v[186:189], v242 offset:54272
	ds_read_b128 v[208:211], v242 offset:55296
	ds_read_b128 v[212:215], v242 offset:56320
	global_load_lds_dwordx4 v[194:195], off
	s_add_i32 m0, s4, 0x2000
	s_add_u32 s40, s40, 0x100080
	v_lshl_add_u64 v[194:195], v[198:199], 0, s[90:91]
	s_addc_u32 s41, s41, 0
	s_add_i32 s4, s5, s57
	global_load_lds_dwordx4 v[194:195], off
	v_lshl_add_u64 v[194:195], s[40:41], 0, v[0:1]
	s_mov_b32 m0, s4
	s_nop 0
	global_load_lds_dwordx4 v[194:195], off
	v_lshl_add_u64 v[194:195], s[40:41], 0, v[190:191]
	s_add_i32 m0, s4, 0x2000
	s_nop 0
	global_load_lds_dwordx4 v[194:195], off
	v_lshl_add_u64 v[194:195], s[38:39], 0, v[202:203]
	s_mov_b32 m0, s54
	s_nop 0
	global_load_lds_dwordx4 v[194:195], off
	v_lshl_add_u64 v[194:195], s[38:39], 0, v[192:193]
	s_mov_b32 m0, s55
	s_nop 0
	global_load_lds_dwordx4 v[194:195], off
	s_waitcnt vmcnt(8)
	s_waitcnt lgkmcnt(0)
	s_setprio 1
	s_barrier
	v_mfma_f32_16x16x32_bf16 v[62:65], v[126:129], v[166:169], v[62:65]
	v_mfma_f32_16x16x32_bf16 v[58:61], v[134:137], v[166:169], v[58:61]
	v_mfma_f32_16x16x32_bf16 v[46:49], v[126:129], v[174:177], v[46:49]
	v_mfma_f32_16x16x32_bf16 v[42:45], v[134:137], v[174:177], v[42:45]
	v_mfma_f32_16x16x32_bf16 v[30:33], v[126:129], v[182:185], v[30:33]
	v_mfma_f32_16x16x32_bf16 v[26:29], v[134:137], v[182:185], v[26:29]
	v_mfma_f32_16x16x32_bf16 v[14:17], v[126:129], v[208:211], v[14:17]
	v_mfma_f32_16x16x32_bf16 v[10:13], v[134:137], v[208:211], v[10:13]
	v_mfma_f32_16x16x32_bf16 v[62:65], v[130:133], v[170:173], v[62:65]
	v_mfma_f32_16x16x32_bf16 v[58:61], v[138:141], v[170:173], v[58:61]
	v_mfma_f32_16x16x32_bf16 v[46:49], v[130:133], v[178:181], v[46:49]
	v_mfma_f32_16x16x32_bf16 v[42:45], v[138:141], v[178:181], v[42:45]
	v_mfma_f32_16x16x32_bf16 v[30:33], v[130:133], v[186:189], v[30:33]
	v_mfma_f32_16x16x32_bf16 v[26:29], v[138:141], v[186:189], v[26:29]
	v_mfma_f32_16x16x32_bf16 v[14:17], v[130:133], v[212:215], v[14:17]
	v_mfma_f32_16x16x32_bf16 v[10:13], v[138:141], v[212:215], v[10:13]
	v_mfma_f32_16x16x32_bf16 v[54:57], v[142:145], v[166:169], v[54:57]
	v_mfma_f32_16x16x32_bf16 v[50:53], v[158:161], v[166:169], v[50:53]
	v_mfma_f32_16x16x32_bf16 v[38:41], v[142:145], v[174:177], v[38:41]
	v_mfma_f32_16x16x32_bf16 v[34:37], v[158:161], v[174:177], v[34:37]
	v_mfma_f32_16x16x32_bf16 v[22:25], v[142:145], v[182:185], v[22:25]
	v_mfma_f32_16x16x32_bf16 v[18:21], v[158:161], v[182:185], v[18:21]
	v_mfma_f32_16x16x32_bf16 v[6:9], v[142:145], v[208:211], v[6:9]
	v_mfma_f32_16x16x32_bf16 v[2:5], v[158:161], v[208:211], v[2:5]
	v_mfma_f32_16x16x32_bf16 v[54:57], v[146:149], v[170:173], v[54:57]
	v_mfma_f32_16x16x32_bf16 v[50:53], v[162:165], v[170:173], v[50:53]
	v_mfma_f32_16x16x32_bf16 v[38:41], v[146:149], v[178:181], v[38:41]
	v_mfma_f32_16x16x32_bf16 v[34:37], v[162:165], v[178:181], v[34:37]
	v_mfma_f32_16x16x32_bf16 v[22:25], v[146:149], v[186:189], v[22:25]
	v_mfma_f32_16x16x32_bf16 v[18:21], v[162:165], v[186:189], v[18:21]
	v_mfma_f32_16x16x32_bf16 v[6:9], v[146:149], v[212:215], v[6:9]
	v_mfma_f32_16x16x32_bf16 v[2:5], v[162:165], v[212:215], v[2:5]
	s_barrier
	s_setprio 0
	s_add_i32 s84, s84, 2
	s_add_u32 s36, s36, 0x100
	s_addc_u32 s37, s37, 0
	s_cmp_gt_u32 s84, 61
	s_cbranch_scc0 .LBB0_915
	s_and_b64 vcc, exec, s[20:21]
	s_cbranch_vccz .LBB0_918
	s_barrier

.LBB0_953:
	s_add_u32 s4, s24, s26
	s_addc_u32 s5, s25, s27
	s_add_u32 s34, s4, 0x100
	s_addc_u32 s35, s5, 0
	s_add_u32 s30, s68, s26
	s_addc_u32 s31, s69, s27
	s_add_u32 s4, s4, 0x180
	s_addc_u32 s5, s5, 0
	s_add_i32 s71, 0, 0x10000
	s_add_i32 s74, 0, 0x14000
	v_add_u32_e32 v146, s71, v229
	v_add_u32_e32 v162, s74, v229
	ds_read_b128 v[134:137], v146
	ds_read_b128 v[138:141], v146 offset:1024
	ds_read_b128 v[142:145], v146 offset:2048
	ds_read_b128 v[146:149], v146 offset:3072
	ds_read_b128 v[150:153], v162
	ds_read_b128 v[154:157], v162 offset:1024
	ds_read_b128 v[158:161], v162 offset:2048
	ds_read_b128 v[162:165], v162 offset:3072
	s_cmpk_eq_i32 s26, 0x1f00
	s_cselect_b32 s29, s65, s5
	s_cselect_b32 s28, s59, s4
	s_cselect_b32 s31, s17, s31
	s_cselect_b32 s30, s58, s30
	s_cselect_b32 s35, s19, s35
	s_cselect_b32 s34, s57, s34
	v_lshl_add_u64 v[194:195], v[122:123], 0, s[26:27]
	s_add_i32 m0, s37, 0xc000
	ds_read_b128 v[166:169], v231
	ds_read_b128 v[170:173], v231 offset:1024
	ds_read_b128 v[174:177], v231 offset:2048
	ds_read_b128 v[178:181], v231 offset:3072
	ds_read_b128 v[182:185], v231 offset:4096
	ds_read_b128 v[186:189], v231 offset:5120
	ds_read_b128 v[190:193], v231 offset:6144
	ds_read_b128 v[212:215], v231 offset:7168
	global_load_lds_dwordx4 v[194:195], off
	v_lshl_add_u64 v[194:195], v[124:125], 0, s[26:27]
	s_add_i32 m0, s37, 0xe000
	s_nop 0
	global_load_lds_dwordx4 v[194:195], off
	s_waitcnt vmcnt(8)
	s_waitcnt lgkmcnt(0)
	s_setprio 1
	s_barrier
	v_mfma_f32_16x16x32_bf16 v[130:133], v[134:137], v[166:169], v[130:133]
	v_mfma_f32_16x16x32_bf16 v[126:129], v[142:145], v[166:169], v[126:129]
	v_mfma_f32_16x16x32_bf16 v[110:113], v[134:137], v[174:177], v[110:113]
	v_mfma_f32_16x16x32_bf16 v[106:109], v[142:145], v[174:177], v[106:109]
	v_mfma_f32_16x16x32_bf16 v[94:97], v[134:137], v[182:185], v[94:97]
	v_mfma_f32_16x16x32_bf16 v[90:93], v[142:145], v[182:185], v[90:93]
	v_mfma_f32_16x16x32_bf16 v[78:81], v[134:137], v[190:193], v[78:81]
	v_mfma_f32_16x16x32_bf16 v[74:77], v[142:145], v[190:193], v[74:77]
	v_mfma_f32_16x16x32_bf16 v[130:133], v[138:141], v[170:173], v[130:133]
	v_mfma_f32_16x16x32_bf16 v[126:129], v[146:149], v[170:173], v[126:129]
	v_mfma_f32_16x16x32_bf16 v[110:113], v[138:141], v[178:181], v[110:113]
	v_mfma_f32_16x16x32_bf16 v[106:109], v[146:149], v[178:181], v[106:109]
	v_mfma_f32_16x16x32_bf16 v[94:97], v[138:141], v[186:189], v[94:97]
	v_mfma_f32_16x16x32_bf16 v[90:93], v[146:149], v[186:189], v[90:93]
	v_mfma_f32_16x16x32_bf16 v[78:81], v[138:141], v[212:215], v[78:81]
	v_mfma_f32_16x16x32_bf16 v[74:77], v[146:149], v[212:215], v[74:77]
	v_mfma_f32_16x16x32_bf16 v[118:121], v[150:153], v[166:169], v[118:121]
	v_mfma_f32_16x16x32_bf16 v[114:117], v[158:161], v[166:169], v[114:117]
	v_mfma_f32_16x16x32_bf16 v[102:105], v[150:153], v[174:177], v[102:105]
	v_mfma_f32_16x16x32_bf16 v[98:101], v[158:161], v[174:177], v[98:101]
	v_mfma_f32_16x16x32_bf16 v[86:89], v[150:153], v[182:185], v[86:89]
	v_mfma_f32_16x16x32_bf16 v[82:85], v[158:161], v[182:185], v[82:85]
	v_mfma_f32_16x16x32_bf16 v[70:73], v[150:153], v[190:193], v[70:73]
	v_mfma_f32_16x16x32_bf16 v[66:69], v[158:161], v[190:193], v[66:69]
	v_mfma_f32_16x16x32_bf16 v[118:121], v[154:157], v[170:173], v[118:121]
	v_mfma_f32_16x16x32_bf16 v[114:117], v[162:165], v[170:173], v[114:117]
	v_mfma_f32_16x16x32_bf16 v[102:105], v[154:157], v[178:181], v[102:105]
	v_mfma_f32_16x16x32_bf16 v[98:101], v[162:165], v[178:181], v[98:101]
	v_mfma_f32_16x16x32_bf16 v[86:89], v[154:157], v[186:189], v[86:89]
	v_mfma_f32_16x16x32_bf16 v[82:85], v[162:165], v[186:189], v[82:85]
	v_mfma_f32_16x16x32_bf16 v[70:73], v[154:157], v[212:215], v[70:73]
	v_mfma_f32_16x16x32_bf16 v[66:69], v[162:165], v[212:215], v[66:69]
	s_barrier
	s_setprio 0
	s_add_i32 s4, s71, s36
	v_lshl_add_u64 v[194:195], s[30:31], 0, v[0:1]
	s_mov_b32 m0, s4
	ds_read_b128 v[166:169], v231 offset:16384
	ds_read_b128 v[170:173], v231 offset:17408
	ds_read_b128 v[174:177], v231 offset:18432
	ds_read_b128 v[178:181], v231 offset:19456
	ds_read_b128 v[182:185], v231 offset:20480
	ds_read_b128 v[186:189], v231 offset:21504
	ds_read_b128 v[190:193], v231 offset:22528
	ds_read_b128 v[212:215], v231 offset:23552
	global_load_lds_dwordx4 v[194:195], off
	s_add_i32 m0, s4, 0x2000
	s_add_u32 s72, s30, 0x100000
	v_lshl_add_u64 v[198:199], s[30:31], 0, v[202:203]
	s_addc_u32 s73, s31, 0
	s_add_i32 s4, s74, s36
	global_load_lds_dwordx4 v[198:199], off
	v_lshl_add_u64 v[216:217], s[72:73], 0, v[0:1]
	s_mov_b32 m0, s4
	s_nop 0
	global_load_lds_dwordx4 v[216:217], off
	v_lshl_add_u64 v[216:217], s[72:73], 0, v[202:203]
	s_add_i32 m0, s4, 0x2000
	s_nop 0
	global_load_lds_dwordx4 v[216:217], off
	v_lshl_add_u64 v[216:217], s[34:35], 0, v[206:207]
	s_mov_b32 m0, s37
	s_nop 0
	global_load_lds_dwordx4 v[216:217], off
	v_lshl_add_u64 v[216:217], s[34:35], 0, v[204:205]
	s_mov_b32 m0, s38
	s_nop 0
	global_load_lds_dwordx4 v[216:217], off
	s_waitcnt vmcnt(8)
	s_waitcnt lgkmcnt(0)
	s_setprio 1
	s_barrier
	v_mfma_f32_16x16x32_bf16 v[62:65], v[134:137], v[166:169], v[62:65]
	v_mfma_f32_16x16x32_bf16 v[58:61], v[142:145], v[166:169], v[58:61]
	v_mfma_f32_16x16x32_bf16 v[46:49], v[134:137], v[174:177], v[46:49]
	v_mfma_f32_16x16x32_bf16 v[42:45], v[142:145], v[174:177], v[42:45]
	v_mfma_f32_16x16x32_bf16 v[30:33], v[134:137], v[182:185], v[30:33]
	v_mfma_f32_16x16x32_bf16 v[26:29], v[142:145], v[182:185], v[26:29]
	v_mfma_f32_16x16x32_bf16 v[14:17], v[134:137], v[190:193], v[14:17]
	v_mfma_f32_16x16x32_bf16 v[10:13], v[142:145], v[190:193], v[10:13]
	v_mfma_f32_16x16x32_bf16 v[62:65], v[138:141], v[170:173], v[62:65]
	v_mfma_f32_16x16x32_bf16 v[58:61], v[146:149], v[170:173], v[58:61]
	v_mfma_f32_16x16x32_bf16 v[46:49], v[138:141], v[178:181], v[46:49]
	v_mfma_f32_16x16x32_bf16 v[42:45], v[146:149], v[178:181], v[42:45]
	v_mfma_f32_16x16x32_bf16 v[30:33], v[138:141], v[186:189], v[30:33]
	v_mfma_f32_16x16x32_bf16 v[26:29], v[146:149], v[186:189], v[26:29]
	v_mfma_f32_16x16x32_bf16 v[14:17], v[138:141], v[212:215], v[14:17]
	v_mfma_f32_16x16x32_bf16 v[10:13], v[146:149], v[212:215], v[10:13]
	v_mfma_f32_16x16x32_bf16 v[54:57], v[150:153], v[166:169], v[54:57]
	v_mfma_f32_16x16x32_bf16 v[50:53], v[158:161], v[166:169], v[50:53]
	v_mfma_f32_16x16x32_bf16 v[38:41], v[150:153], v[174:177], v[38:41]
	v_mfma_f32_16x16x32_bf16 v[34:37], v[158:161], v[174:177], v[34:37]
	v_mfma_f32_16x16x32_bf16 v[22:25], v[150:153], v[182:185], v[22:25]
	v_mfma_f32_16x16x32_bf16 v[18:21], v[158:161], v[182:185], v[18:21]
	v_mfma_f32_16x16x32_bf16 v[6:9], v[150:153], v[190:193], v[6:9]
	v_mfma_f32_16x16x32_bf16 v[2:5], v[158:161], v[190:193], v[2:5]
	v_mfma_f32_16x16x32_bf16 v[54:57], v[154:157], v[170:173], v[54:57]
	v_mfma_f32_16x16x32_bf16 v[50:53], v[162:165], v[170:173], v[50:53]
	v_mfma_f32_16x16x32_bf16 v[38:41], v[154:157], v[178:181], v[38:41]
	v_mfma_f32_16x16x32_bf16 v[34:37], v[162:165], v[178:181], v[34:37]
	v_mfma_f32_16x16x32_bf16 v[22:25], v[154:157], v[186:189], v[22:25]
	v_mfma_f32_16x16x32_bf16 v[18:21], v[162:165], v[186:189], v[18:21]
	v_mfma_f32_16x16x32_bf16 v[6:9], v[154:157], v[212:215], v[6:9]
	v_mfma_f32_16x16x32_bf16 v[2:5], v[162:165], v[212:215], v[2:5]
	s_barrier
	s_setprio 0
	s_add_i32 s4, 0, 0x18000
	s_add_i32 s5, 0, 0x1c000
	v_add_u32_e32 v146, s4, v229
	v_add_u32_e32 v162, s5, v229
	ds_read_b128 v[134:137], v146
	ds_read_b128 v[138:141], v146 offset:1024
	ds_read_b128 v[142:145], v146 offset:2048
	ds_read_b128 v[146:149], v146 offset:3072
	ds_read_b128 v[150:153], v162
	ds_read_b128 v[154:157], v162 offset:1024
	ds_read_b128 v[158:161], v162 offset:2048
	ds_read_b128 v[162:165], v162 offset:3072
	s_add_u32 s34, s34, 0x100000
	s_addc_u32 s35, s35, 0
	s_mov_b32 m0, s39
	v_lshl_add_u64 v[216:217], s[34:35], 0, v[206:207]
	ds_read_b128 v[166:169], v231 offset:32768
	ds_read_b128 v[170:173], v231 offset:33792
	ds_read_b128 v[174:177], v231 offset:34816
	ds_read_b128 v[178:181], v231 offset:35840
	ds_read_b128 v[182:185], v231 offset:36864
	ds_read_b128 v[186:189], v231 offset:37888
	ds_read_b128 v[190:193], v231 offset:38912
	ds_read_b128 v[212:215], v231 offset:39936
	global_load_lds_dwordx4 v[216:217], off
	v_lshl_add_u64 v[216:217], s[34:35], 0, v[204:205]
	s_mov_b32 m0, s40
	s_nop 0
	global_load_lds_dwordx4 v[216:217], off
	s_waitcnt vmcnt(8)
	s_waitcnt lgkmcnt(0)
	s_setprio 1
	s_barrier
	v_mfma_f32_16x16x32_bf16 v[130:133], v[134:137], v[166:169], v[130:133]
	v_mfma_f32_16x16x32_bf16 v[126:129], v[142:145], v[166:169], v[126:129]
	v_mfma_f32_16x16x32_bf16 v[110:113], v[134:137], v[174:177], v[110:113]
	v_mfma_f32_16x16x32_bf16 v[106:109], v[142:145], v[174:177], v[106:109]
	v_mfma_f32_16x16x32_bf16 v[94:97], v[134:137], v[182:185], v[94:97]
	v_mfma_f32_16x16x32_bf16 v[90:93], v[142:145], v[182:185], v[90:93]
	v_mfma_f32_16x16x32_bf16 v[78:81], v[134:137], v[190:193], v[78:81]
	v_mfma_f32_16x16x32_bf16 v[74:77], v[142:145], v[190:193], v[74:77]
	v_mfma_f32_16x16x32_bf16 v[130:133], v[138:141], v[170:173], v[130:133]
	v_mfma_f32_16x16x32_bf16 v[126:129], v[146:149], v[170:173], v[126:129]
	v_mfma_f32_16x16x32_bf16 v[110:113], v[138:141], v[178:181], v[110:113]
	v_mfma_f32_16x16x32_bf16 v[106:109], v[146:149], v[178:181], v[106:109]
	v_mfma_f32_16x16x32_bf16 v[94:97], v[138:141], v[186:189], v[94:97]
	v_mfma_f32_16x16x32_bf16 v[90:93], v[146:149], v[186:189], v[90:93]
	v_mfma_f32_16x16x32_bf16 v[78:81], v[138:141], v[212:215], v[78:81]
	v_mfma_f32_16x16x32_bf16 v[74:77], v[146:149], v[212:215], v[74:77]
	v_mfma_f32_16x16x32_bf16 v[118:121], v[150:153], v[166:169], v[118:121]
	v_mfma_f32_16x16x32_bf16 v[114:117], v[158:161], v[166:169], v[114:117]
	v_mfma_f32_16x16x32_bf16 v[102:105], v[150:153], v[174:177], v[102:105]
	v_mfma_f32_16x16x32_bf16 v[98:101], v[158:161], v[174:177], v[98:101]
	v_mfma_f32_16x16x32_bf16 v[86:89], v[150:153], v[182:185], v[86:89]
	v_mfma_f32_16x16x32_bf16 v[82:85], v[158:161], v[182:185], v[82:85]
	v_mfma_f32_16x16x32_bf16 v[70:73], v[150:153], v[190:193], v[70:73]
	v_mfma_f32_16x16x32_bf16 v[66:69], v[158:161], v[190:193], v[66:69]
	v_mfma_f32_16x16x32_bf16 v[118:121], v[154:157], v[170:173], v[118:121]
	v_mfma_f32_16x16x32_bf16 v[114:117], v[162:165], v[170:173], v[114:117]
	v_mfma_f32_16x16x32_bf16 v[102:105], v[154:157], v[178:181], v[102:105]
	v_mfma_f32_16x16x32_bf16 v[98:101], v[162:165], v[178:181], v[98:101]
	v_mfma_f32_16x16x32_bf16 v[86:89], v[154:157], v[186:189], v[86:89]
	v_mfma_f32_16x16x32_bf16 v[82:85], v[162:165], v[186:189], v[82:85]
	v_mfma_f32_16x16x32_bf16 v[70:73], v[154:157], v[212:215], v[70:73]
	v_mfma_f32_16x16x32_bf16 v[66:69], v[162:165], v[212:215], v[66:69]
	s_barrier
	s_setprio 0
	s_add_i32 s4, s4, s36
	v_lshl_add_u64 v[194:195], v[194:195], 0, s[90:91]
	s_mov_b32 m0, s4
	ds_read_b128 v[166:169], v231 offset:49152
	ds_read_b128 v[170:173], v231 offset:50176
	ds_read_b128 v[174:177], v231 offset:51200
	ds_read_b128 v[178:181], v231 offset:52224
	ds_read_b128 v[182:185], v231 offset:53248
	ds_read_b128 v[186:189], v231 offset:54272
	ds_read_b128 v[190:193], v231 offset:55296
	ds_read_b128 v[212:215], v231 offset:56320
	global_load_lds_dwordx4 v[194:195], off
	s_add_i32 m0, s4, 0x2000
	s_add_u32 s30, s30, 0x100080
	v_lshl_add_u64 v[194:195], v[198:199], 0, s[90:91]
	s_addc_u32 s31, s31, 0
	s_add_i32 s4, s5, s36
	global_load_lds_dwordx4 v[194:195], off
	v_lshl_add_u64 v[194:195], s[30:31], 0, v[0:1]
	s_mov_b32 m0, s4
	s_nop 0
	global_load_lds_dwordx4 v[194:195], off
	v_lshl_add_u64 v[194:195], s[30:31], 0, v[202:203]
	s_add_i32 m0, s4, 0x2000
	s_nop 0
	global_load_lds_dwordx4 v[194:195], off
	v_lshl_add_u64 v[194:195], s[28:29], 0, v[206:207]
	s_mov_b32 m0, s41
	s_nop 0
	global_load_lds_dwordx4 v[194:195], off
	v_lshl_add_u64 v[194:195], s[28:29], 0, v[204:205]
	s_mov_b32 m0, s42
	s_nop 0
	global_load_lds_dwordx4 v[194:195], off
	s_waitcnt vmcnt(8)
	s_waitcnt lgkmcnt(0)
	s_setprio 1
	s_barrier
	v_mfma_f32_16x16x32_bf16 v[62:65], v[134:137], v[166:169], v[62:65]
	v_mfma_f32_16x16x32_bf16 v[58:61], v[142:145], v[166:169], v[58:61]
	v_mfma_f32_16x16x32_bf16 v[46:49], v[134:137], v[174:177], v[46:49]
	v_mfma_f32_16x16x32_bf16 v[42:45], v[142:145], v[174:177], v[42:45]
	v_mfma_f32_16x16x32_bf16 v[30:33], v[134:137], v[182:185], v[30:33]
	v_mfma_f32_16x16x32_bf16 v[26:29], v[142:145], v[182:185], v[26:29]
	v_mfma_f32_16x16x32_bf16 v[14:17], v[134:137], v[190:193], v[14:17]
	v_mfma_f32_16x16x32_bf16 v[10:13], v[142:145], v[190:193], v[10:13]
	v_mfma_f32_16x16x32_bf16 v[62:65], v[138:141], v[170:173], v[62:65]
	v_mfma_f32_16x16x32_bf16 v[58:61], v[146:149], v[170:173], v[58:61]
	v_mfma_f32_16x16x32_bf16 v[46:49], v[138:141], v[178:181], v[46:49]
	v_mfma_f32_16x16x32_bf16 v[42:45], v[146:149], v[178:181], v[42:45]
	v_mfma_f32_16x16x32_bf16 v[30:33], v[138:141], v[186:189], v[30:33]
	v_mfma_f32_16x16x32_bf16 v[26:29], v[146:149], v[186:189], v[26:29]
	v_mfma_f32_16x16x32_bf16 v[14:17], v[138:141], v[212:215], v[14:17]
	v_mfma_f32_16x16x32_bf16 v[10:13], v[146:149], v[212:215], v[10:13]
	v_mfma_f32_16x16x32_bf16 v[54:57], v[150:153], v[166:169], v[54:57]
	v_mfma_f32_16x16x32_bf16 v[50:53], v[158:161], v[166:169], v[50:53]
	v_mfma_f32_16x16x32_bf16 v[38:41], v[150:153], v[174:177], v[38:41]
	v_mfma_f32_16x16x32_bf16 v[34:37], v[158:161], v[174:177], v[34:37]
	v_mfma_f32_16x16x32_bf16 v[22:25], v[150:153], v[182:185], v[22:25]
	v_mfma_f32_16x16x32_bf16 v[18:21], v[158:161], v[182:185], v[18:21]
	v_mfma_f32_16x16x32_bf16 v[6:9], v[150:153], v[190:193], v[6:9]
	v_mfma_f32_16x16x32_bf16 v[2:5], v[158:161], v[190:193], v[2:5]
	v_mfma_f32_16x16x32_bf16 v[54:57], v[154:157], v[170:173], v[54:57]
	v_mfma_f32_16x16x32_bf16 v[50:53], v[162:165], v[170:173], v[50:53]
	v_mfma_f32_16x16x32_bf16 v[38:41], v[154:157], v[178:181], v[38:41]
	v_mfma_f32_16x16x32_bf16 v[34:37], v[162:165], v[178:181], v[34:37]
	v_mfma_f32_16x16x32_bf16 v[22:25], v[154:157], v[186:189], v[22:25]
	v_mfma_f32_16x16x32_bf16 v[18:21], v[162:165], v[186:189], v[18:21]
	v_mfma_f32_16x16x32_bf16 v[6:9], v[154:157], v[212:215], v[6:9]
	v_mfma_f32_16x16x32_bf16 v[2:5], v[162:165], v[212:215], v[2:5]
	s_barrier
	s_setprio 0
	s_add_i32 s70, s70, 2
	s_add_u32 s26, s26, 0x100
	s_addc_u32 s27, s27, 0
	s_cmp_gt_u32 s70, 61
	s_cbranch_scc0 .LBB0_953
	s_and_b64 vcc, exec, s[14:15]
	s_cbranch_vccz .LBB0_956
	s_barrier
